# MFMA issue order inside each 16-MFMA group changed to same-accumulator pairs back to back (k0,k1) on top of v1
# speedup vs baseline: 1.0080x; 1.0080x over previous
; #define PG8_STAGE(bufoff, gbase, voff) do { _Pragma("unroll") for (int _i = 0; _i < 2; ++_i) \
;         __builtin_amdgcn_global_load_lds((const unsigned*)((const char*)(gbase) + (voff)[_i]), (LAS unsigned*)(lds + (bufoff) + ldsw + _i * 8192), 16, 0, 0); } while (0)
; #define PG8_LDA(dst, b, h) do { _Pragma("unroll") for (int m = 0; m < 4; ++m) _Pragma("unroll") for (int k = 0; k < 2; ++k) dst[m][k] = *(const LAS bf16x8*)(lds + PG8_SA(b, h) + aoff + m * 2048 + k * 1024); } while (0)
; #define PG8_LDB(dst, b, h) do { _Pragma("unroll") for (int n = 0; n < 2; ++n) _Pragma("unroll") for (int k = 0; k < 2; ++k) dst[n][k] = *(const LAS bf16x8*)(lds + PG8_SB(b, h) + boff + n * 2048 + k * 1024); } while (0)
; #define PG8_MMA(ai, bj, At, Bt) do { __builtin_amdgcn_s_setprio(1); _Pragma("unroll") for (int m = 0; m < 4; ++m) _Pragma("unroll") for (int n = 0; n < 2; ++n) _Pragma("unroll") for (int k = 0; k < 2; ++k) \
;         acc[ai][bj][m][n] = __builtin_amdgcn_mfma_f32_16x16x32_bf16(Bt[n][k], At[m][k], acc[ai][bj][m][n], 0, 0, 0); __builtin_amdgcn_s_setprio(0); } while (0)
; #define PG8_WAIT_L(n) asm volatile("s_waitcnt lgkmcnt(" #n ")" ::: "memory")
; #define PG8_BAR __builtin_amdgcn_s_barrier()
; #define PG8_SCHED __builtin_amdgcn_sched_barrier(0)
; template <class Epi, class Sched>
; __device__ __forceinline__ void gemm_phase(LAS unsigned char* lds, const Gemm g, const Sched& S, const Epi& E) {
;     ...
;         for (int t = 0; t < nt; t += 2) {
;             const bool last = (t == nt - 2);
;             const char* a1 = cA + (size_t)(t + 1) * kstep;
;             const char* a2 = last ? nA : cA + (size_t)(t + 2) * kstep; const char* b2 = last ? nB : cB + (size_t)(t + 2) * kstep;
;             const char* a3 = a2 + kstep; const char* b3 = b2 + kstep;
;             PG8_LDB(B0, 0, 0); PG8_SCHED; PG8_LDA(At, 0, 0); PG8_STAGE(PG8_SA(1, 1), a1 + hstep, voffA);
;             PG8_WAIT_L(8); PG8_BAR; PG8_WAIT_L(0); PG8_MMA(0, 0, At, B0); PG8_BAR; PG8_SCHED;
;             PG8_LDB(B1, 0, 1); PG8_STAGE(PG8_SB(0, 0), b2, voffB);
;             PG8_BAR; PG8_WAIT_L(0); PG8_MMA(0, 1, At, B1); PG8_BAR;
;             PG8_LDA(At, 0, 1); PG8_STAGE(PG8_SA(0, 0), a2, voffA);
;             PG8_BAR; PG8_WAIT_L(0); PG8_MMA(1, 0, At, B0); PG8_BAR; PG8_SCHED;
.LBB0_165:
	s_add_u32 s24, s38, 0xfffc0080
	s_addc_u32 s25, s39, -1
	s_add_i32 vcc_hi, 0, 0x10000
	v_add_u32_e32 v166, vcc_hi, v167
	ds_read_b128 v[142:145], v166
	ds_read_b128 v[162:165], v166 offset:1024
	ds_read_b128 v[182:185], v166 offset:2048
	ds_read_b128 v[186:189], v166 offset:3072
	s_cmp_eq_u32 s50, 12
	s_cselect_b32 s61, s34, s25
	s_cselect_b32 s60, s45, s24
	s_cselect_b32 s49, s43, s35
	s_cselect_b32 s48, s79, vcc_lo
	v_lshl_add_u64 v[222:223], s[38:39], 0, v[140:141]
	s_add_i32 m0, s93, 0xc000
	ds_read_b128 v[190:193], v169
	ds_read_b128 v[194:197], v169 offset:1024
	ds_read_b128 v[198:201], v169 offset:2048
	ds_read_b128 v[202:205], v169 offset:3072
	ds_read_b128 v[206:209], v169 offset:4096
	ds_read_b128 v[210:213], v169 offset:5120
	ds_read_b128 v[214:217], v169 offset:6144
	ds_read_b128 v[218:221], v169 offset:7168
	global_load_lds_dwordx4 v[222:223], off
	v_lshl_add_u64 v[222:223], s[38:39], 0, v[138:139]
	s_add_i32 m0, s93, 0xe000
	s_nop 0
	global_load_lds_dwordx4 v[222:223], off
	s_waitcnt lgkmcnt(8)
	s_barrier
	s_waitcnt lgkmcnt(0)
	s_setprio 1
	s_waitcnt lgkmcnt(0)
	v_mfma_f32_16x16x32_bf16 v[126:129], v[142:145], v[190:193], v[126:129]
	v_mfma_f32_16x16x32_bf16 v[126:129], v[162:165], v[194:197], v[126:129]
	v_mfma_f32_16x16x32_bf16 v[122:125], v[182:185], v[190:193], v[122:125]
	v_mfma_f32_16x16x32_bf16 v[122:125], v[186:189], v[194:197], v[122:125]
	v_mfma_f32_16x16x32_bf16 v[110:113], v[142:145], v[198:201], v[110:113]
	v_mfma_f32_16x16x32_bf16 v[110:113], v[162:165], v[202:205], v[110:113]
	v_mfma_f32_16x16x32_bf16 v[106:109], v[182:185], v[198:201], v[106:109]
	v_mfma_f32_16x16x32_bf16 v[106:109], v[186:189], v[202:205], v[106:109]
	v_mfma_f32_16x16x32_bf16 v[94:97], v[142:145], v[206:209], v[94:97]
	v_mfma_f32_16x16x32_bf16 v[94:97], v[162:165], v[210:213], v[94:97]
	v_mfma_f32_16x16x32_bf16 v[90:93], v[182:185], v[206:209], v[90:93]
	v_mfma_f32_16x16x32_bf16 v[90:93], v[186:189], v[210:213], v[90:93]
	v_mfma_f32_16x16x32_bf16 v[78:81], v[142:145], v[214:217], v[78:81]
	v_mfma_f32_16x16x32_bf16 v[78:81], v[162:165], v[218:221], v[78:81]
	v_mfma_f32_16x16x32_bf16 v[74:77], v[182:185], v[214:217], v[74:77]
	v_mfma_f32_16x16x32_bf16 v[74:77], v[186:189], v[218:221], v[74:77]
	s_setprio 0
	s_barrier
	s_add_i32 s51, 0, 0x14000
	s_add_i32 s24, vcc_hi, s86
	v_add_u32_e32 v166, s51, v167
	v_lshl_add_u64 v[238:239], s[48:49], 0, v[134:135]
	s_mov_b32 m0, s24
	ds_read_b128 v[222:225], v166
	ds_read_b128 v[226:229], v166 offset:1024
	ds_read_b128 v[230:233], v166 offset:2048
	ds_read_b128 v[234:237], v166 offset:3072
	global_load_lds_dwordx4 v[238:239], off
	v_lshl_add_u64 v[240:241], s[48:49], 0, v[130:131]
	s_add_i32 m0, s24, 0x2000
	s_nop 0
	global_load_lds_dwordx4 v[240:241], off
	s_barrier
	s_waitcnt lgkmcnt(0)
	s_setprio 1
	s_waitcnt lgkmcnt(0)
	v_mfma_f32_16x16x32_bf16 v[118:121], v[222:225], v[190:193], v[118:121]
	v_mfma_f32_16x16x32_bf16 v[118:121], v[226:229], v[194:197], v[118:121]
	v_mfma_f32_16x16x32_bf16 v[114:117], v[230:233], v[190:193], v[114:117]
	v_mfma_f32_16x16x32_bf16 v[114:117], v[234:237], v[194:197], v[114:117]
	v_mfma_f32_16x16x32_bf16 v[102:105], v[222:225], v[198:201], v[102:105]
	v_mfma_f32_16x16x32_bf16 v[102:105], v[226:229], v[202:205], v[102:105]
	v_mfma_f32_16x16x32_bf16 v[98:101], v[230:233], v[198:201], v[98:101]
	v_mfma_f32_16x16x32_bf16 v[98:101], v[234:237], v[202:205], v[98:101]
	v_mfma_f32_16x16x32_bf16 v[86:89], v[222:225], v[206:209], v[86:89]
	v_mfma_f32_16x16x32_bf16 v[86:89], v[226:229], v[210:213], v[86:89]
	v_mfma_f32_16x16x32_bf16 v[82:85], v[230:233], v[206:209], v[82:85]
	v_mfma_f32_16x16x32_bf16 v[82:85], v[234:237], v[210:213], v[82:85]
	v_mfma_f32_16x16x32_bf16 v[70:73], v[222:225], v[214:217], v[70:73]
	v_mfma_f32_16x16x32_bf16 v[70:73], v[226:229], v[218:221], v[70:73]
	v_mfma_f32_16x16x32_bf16 v[66:69], v[230:233], v[214:217], v[66:69]
	v_mfma_f32_16x16x32_bf16 v[66:69], v[234:237], v[218:221], v[66:69]
	s_setprio 0
	s_mov_b32 m0, s93
	v_lshl_add_u64 v[242:243], s[60:61], 0, v[136:137]
	s_barrier
	ds_read_b128 v[190:193], v169 offset:16384
	ds_read_b128 v[194:197], v169 offset:17408
	ds_read_b128 v[198:201], v169 offset:18432
	ds_read_b128 v[202:205], v169 offset:19456
	ds_read_b128 v[206:209], v169 offset:20480
	ds_read_b128 v[210:213], v169 offset:21504
	ds_read_b128 v[214:217], v169 offset:22528
	ds_read_b128 v[218:221], v169 offset:23552
	global_load_lds_dwordx4 v[242:243], off
	v_lshl_add_u64 v[244:245], s[60:61], 0, v[132:133]
	s_mov_b32 m0, s98
	s_nop 0
	global_load_lds_dwordx4 v[244:245], off
	s_barrier
	s_waitcnt lgkmcnt(0)
	s_setprio 1
	s_waitcnt lgkmcnt(0)
	v_mfma_f32_16x16x32_bf16 v[62:65], v[142:145], v[190:193], v[62:65]
	v_mfma_f32_16x16x32_bf16 v[62:65], v[162:165], v[194:197], v[62:65]
	v_mfma_f32_16x16x32_bf16 v[58:61], v[182:185], v[190:193], v[58:61]
	v_mfma_f32_16x16x32_bf16 v[58:61], v[186:189], v[194:197], v[58:61]
	v_mfma_f32_16x16x32_bf16 v[46:49], v[142:145], v[198:201], v[46:49]
	v_mfma_f32_16x16x32_bf16 v[46:49], v[162:165], v[202:205], v[46:49]
	v_mfma_f32_16x16x32_bf16 v[42:45], v[182:185], v[198:201], v[42:45]
	v_mfma_f32_16x16x32_bf16 v[42:45], v[186:189], v[202:205], v[42:45]
	v_mfma_f32_16x16x32_bf16 v[30:33], v[142:145], v[206:209], v[30:33]
	v_mfma_f32_16x16x32_bf16 v[30:33], v[162:165], v[210:213], v[30:33]
	v_mfma_f32_16x16x32_bf16 v[26:29], v[182:185], v[206:209], v[26:29]
	v_mfma_f32_16x16x32_bf16 v[26:29], v[186:189], v[210:213], v[26:29]
	v_mfma_f32_16x16x32_bf16 v[14:17], v[142:145], v[214:217], v[14:17]
	v_mfma_f32_16x16x32_bf16 v[14:17], v[162:165], v[218:221], v[14:17]
	v_mfma_f32_16x16x32_bf16 v[10:13], v[182:185], v[214:217], v[10:13]
	v_mfma_f32_16x16x32_bf16 v[10:13], v[186:189], v[218:221], v[10:13]
	s_setprio 0
	s_barrier
; #define PG8_STAGE(bufoff, gbase, voff) do { _Pragma("unroll") for (int _i = 0; _i < 2; ++_i) \
;         __builtin_amdgcn_global_load_lds((const unsigned*)((const char*)(gbase) + (voff)[_i]), (LAS unsigned*)(lds + (bufoff) + ldsw + _i * 8192), 16, 0, 0); } while (0)
; #define PG8_LDA(dst, b, h) do { _Pragma("unroll") for (int m = 0; m < 4; ++m) _Pragma("unroll") for (int k = 0; k < 2; ++k) dst[m][k] = *(const LAS bf16x8*)(lds + PG8_SA(b, h) + aoff + m * 2048 + k * 1024); } while (0)
; #define PG8_LDB(dst, b, h) do { _Pragma("unroll") for (int n = 0; n < 2; ++n) _Pragma("unroll") for (int k = 0; k < 2; ++k) dst[n][k] = *(const LAS bf16x8*)(lds + PG8_SB(b, h) + boff + n * 2048 + k * 1024); } while (0)
; #define PG8_MMA(ai, bj, At, Bt) do { __builtin_amdgcn_s_setprio(1); _Pragma("unroll") for (int m = 0; m < 4; ++m) _Pragma("unroll") for (int n = 0; n < 2; ++n) _Pragma("unroll") for (int k = 0; k < 2; ++k) \
;         acc[ai][bj][m][n] = __builtin_amdgcn_mfma_f32_16x16x32_bf16(Bt[n][k], At[m][k], acc[ai][bj][m][n], 0, 0, 0); __builtin_amdgcn_s_setprio(0); } while (0)
; #define PG8_WAIT_V(n) asm volatile("s_waitcnt vmcnt(" #n ")" ::: "memory")
; #define PG8_WAIT_L(n) asm volatile("s_waitcnt lgkmcnt(" #n ")" ::: "memory")
; #define PG8_BAR __builtin_amdgcn_s_barrier()
; #define PG8_SCHED __builtin_amdgcn_sched_barrier(0)
; template <class Epi, class Sched>
; __device__ __forceinline__ void gemm_phase(LAS unsigned char* lds, const Gemm g, const Sched& S, const Epi& E) {
;     ...
;             PG8_STAGE(PG8_SB(0, 1), b2 + hstep, voffB);
;             PG8_WAIT_V(6); PG8_BAR; PG8_MMA(1, 1, At, B1); PG8_BAR;
;             PG8_LDB(B0, 1, 0); PG8_SCHED; PG8_LDA(At, 1, 0); PG8_STAGE(PG8_SA(0, 1), a2 + hstep, voffA);
;             PG8_WAIT_L(8); PG8_BAR; PG8_WAIT_L(0); PG8_MMA(0, 0, At, B0); PG8_BAR; PG8_SCHED;
;             PG8_LDB(B1, 1, 1); PG8_STAGE(PG8_SB(1, 0), b3, voffB);
;             PG8_BAR; PG8_WAIT_L(0); PG8_MMA(0, 1, At, B1); PG8_BAR;
	s_add_u32 s24, s48, 0x40000
	s_addc_u32 s25, s49, 0
	s_add_i32 s51, s51, s86
	v_lshl_add_u64 v[142:143], s[24:25], 0, v[134:135]
	s_mov_b32 m0, s51
	s_nop 0
	global_load_lds_dwordx4 v[142:143], off
	v_lshl_add_u64 v[142:143], s[24:25], 0, v[130:131]
	s_add_i32 m0, s51, 0x2000
	s_nop 0
	global_load_lds_dwordx4 v[142:143], off
	s_waitcnt vmcnt(6)
	s_barrier
	s_setprio 1
	v_mfma_f32_16x16x32_bf16 v[54:57], v[222:225], v[190:193], v[54:57]
	v_mfma_f32_16x16x32_bf16 v[54:57], v[226:229], v[194:197], v[54:57]
	v_mfma_f32_16x16x32_bf16 v[50:53], v[230:233], v[190:193], v[50:53]
	v_mfma_f32_16x16x32_bf16 v[50:53], v[234:237], v[194:197], v[50:53]
	v_mfma_f32_16x16x32_bf16 v[38:41], v[222:225], v[198:201], v[38:41]
	v_mfma_f32_16x16x32_bf16 v[38:41], v[226:229], v[202:205], v[38:41]
	v_mfma_f32_16x16x32_bf16 v[34:37], v[230:233], v[198:201], v[34:37]
	v_mfma_f32_16x16x32_bf16 v[34:37], v[234:237], v[202:205], v[34:37]
	v_mfma_f32_16x16x32_bf16 v[22:25], v[222:225], v[206:209], v[22:25]
	v_mfma_f32_16x16x32_bf16 v[22:25], v[226:229], v[210:213], v[22:25]
	v_mfma_f32_16x16x32_bf16 v[18:21], v[230:233], v[206:209], v[18:21]
	v_mfma_f32_16x16x32_bf16 v[18:21], v[234:237], v[210:213], v[18:21]
	v_mfma_f32_16x16x32_bf16 v[6:9], v[222:225], v[214:217], v[6:9]
	v_mfma_f32_16x16x32_bf16 v[6:9], v[226:229], v[218:221], v[6:9]
	v_mfma_f32_16x16x32_bf16 v[2:5], v[230:233], v[214:217], v[2:5]
	v_mfma_f32_16x16x32_bf16 v[2:5], v[234:237], v[218:221], v[2:5]
	s_setprio 0
	s_add_i32 s51, 0, 0x18000
	v_add_u32_e32 v166, s51, v167
	s_barrier
	ds_read_b128 v[142:145], v166
	ds_read_b128 v[162:165], v166 offset:1024
	ds_read_b128 v[182:185], v166 offset:2048
	ds_read_b128 v[186:189], v166 offset:3072
	s_add_u32 s24, s60, 0x40000
	s_addc_u32 s25, s61, 0
	s_mov_b32 m0, s99
	v_lshl_add_u64 v[222:223], s[24:25], 0, v[136:137]
	ds_read_b128 v[190:193], v169 offset:32768
	ds_read_b128 v[194:197], v169 offset:33792
	ds_read_b128 v[198:201], v169 offset:34816
	ds_read_b128 v[202:205], v169 offset:35840
	ds_read_b128 v[206:209], v169 offset:36864
	ds_read_b128 v[210:213], v169 offset:37888
	ds_read_b128 v[214:217], v169 offset:38912
	ds_read_b128 v[218:221], v169 offset:39936
	global_load_lds_dwordx4 v[222:223], off
	v_lshl_add_u64 v[222:223], s[24:25], 0, v[132:133]
	s_mov_b32 m0, s94
	s_nop 0
	global_load_lds_dwordx4 v[222:223], off
	s_waitcnt lgkmcnt(8)
	s_barrier
	s_waitcnt lgkmcnt(0)
	s_setprio 1
	s_waitcnt lgkmcnt(0)
	v_mfma_f32_16x16x32_bf16 v[126:129], v[142:145], v[190:193], v[126:129]
	v_mfma_f32_16x16x32_bf16 v[126:129], v[162:165], v[194:197], v[126:129]
	v_mfma_f32_16x16x32_bf16 v[122:125], v[182:185], v[190:193], v[122:125]
	v_mfma_f32_16x16x32_bf16 v[122:125], v[186:189], v[194:197], v[122:125]
	v_mfma_f32_16x16x32_bf16 v[110:113], v[142:145], v[198:201], v[110:113]
	v_mfma_f32_16x16x32_bf16 v[110:113], v[162:165], v[202:205], v[110:113]
	v_mfma_f32_16x16x32_bf16 v[106:109], v[182:185], v[198:201], v[106:109]
	v_mfma_f32_16x16x32_bf16 v[106:109], v[186:189], v[202:205], v[106:109]
	v_mfma_f32_16x16x32_bf16 v[94:97], v[142:145], v[206:209], v[94:97]
	v_mfma_f32_16x16x32_bf16 v[94:97], v[162:165], v[210:213], v[94:97]
	v_mfma_f32_16x16x32_bf16 v[90:93], v[182:185], v[206:209], v[90:93]
	v_mfma_f32_16x16x32_bf16 v[90:93], v[186:189], v[210:213], v[90:93]
	v_mfma_f32_16x16x32_bf16 v[78:81], v[142:145], v[214:217], v[78:81]
	v_mfma_f32_16x16x32_bf16 v[78:81], v[162:165], v[218:221], v[78:81]
	v_mfma_f32_16x16x32_bf16 v[74:77], v[182:185], v[214:217], v[74:77]
	v_mfma_f32_16x16x32_bf16 v[74:77], v[186:189], v[218:221], v[74:77]
	s_setprio 0
	s_barrier
	s_add_i32 s60, 0, 0x1c000
	s_add_i32 s24, s51, s86
	v_add_u32_e32 v166, s60, v167
	v_lshl_add_u64 v[238:239], v[238:239], 0, s[12:13]
	s_mov_b32 m0, s24
	ds_read_b128 v[222:225], v166
	ds_read_b128 v[226:229], v166 offset:1024
	ds_read_b128 v[230:233], v166 offset:2048
	ds_read_b128 v[234:237], v166 offset:3072
	global_load_lds_dwordx4 v[238:239], off
	v_lshl_add_u64 v[238:239], v[240:241], 0, s[12:13]
	s_add_i32 m0, s24, 0x2000
	s_nop 0
	global_load_lds_dwordx4 v[238:239], off
	s_barrier
; #define PG8_STAGE(bufoff, gbase, voff) do { _Pragma("unroll") for (int _i = 0; _i < 2; ++_i) \
;         __builtin_amdgcn_global_load_lds((const unsigned*)((const char*)(gbase) + (voff)[_i]), (LAS unsigned*)(lds + (bufoff) + ldsw + _i * 8192), 16, 0, 0); } while (0)
; #define PG8_LDA(dst, b, h) do { _Pragma("unroll") for (int m = 0; m < 4; ++m) _Pragma("unroll") for (int k = 0; k < 2; ++k) dst[m][k] = *(const LAS bf16x8*)(lds + PG8_SA(b, h) + aoff + m * 2048 + k * 1024); } while (0)
; #define PG8_MMA(ai, bj, At, Bt) do { __builtin_amdgcn_s_setprio(1); _Pragma("unroll") for (int m = 0; m < 4; ++m) _Pragma("unroll") for (int n = 0; n < 2; ++n) _Pragma("unroll") for (int k = 0; k < 2; ++k) \
;         acc[ai][bj][m][n] = __builtin_amdgcn_mfma_f32_16x16x32_bf16(Bt[n][k], At[m][k], acc[ai][bj][m][n], 0, 0, 0); __builtin_amdgcn_s_setprio(0); } while (0)
; #define PG8_WAIT_V(n) asm volatile("s_waitcnt vmcnt(" #n ")" ::: "memory")
; #define PG8_WAIT_L(n) asm volatile("s_waitcnt lgkmcnt(" #n ")" ::: "memory")
; #define PG8_BAR __builtin_amdgcn_s_barrier()
; #define PG8_SCHED __builtin_amdgcn_sched_barrier(0)
; template <class Epi, class Sched>
; __device__ __forceinline__ void gemm_phase(LAS unsigned char* lds, const Gemm g, const Sched& S, const Epi& E) {
;     ...
;             PG8_LDA(At, 1, 1); PG8_STAGE(PG8_SA(1, 0), a3, voffA);
;             PG8_BAR; PG8_WAIT_L(0); PG8_MMA(1, 0, At, B0); PG8_BAR; PG8_SCHED;
;             PG8_STAGE(PG8_SB(1, 1), b3 + hstep, voffB);
;             PG8_WAIT_V(6); PG8_BAR; PG8_MMA(1, 1, At, B1); PG8_BAR;
;         }
;         if (wr == 0) PG8_BAR;
	s_waitcnt lgkmcnt(0)
	s_setprio 1
	s_waitcnt lgkmcnt(0)
	v_mfma_f32_16x16x32_bf16 v[118:121], v[222:225], v[190:193], v[118:121]
	v_mfma_f32_16x16x32_bf16 v[118:121], v[226:229], v[194:197], v[118:121]
	v_mfma_f32_16x16x32_bf16 v[114:117], v[230:233], v[190:193], v[114:117]
	v_mfma_f32_16x16x32_bf16 v[114:117], v[234:237], v[194:197], v[114:117]
	v_mfma_f32_16x16x32_bf16 v[102:105], v[222:225], v[198:201], v[102:105]
	v_mfma_f32_16x16x32_bf16 v[102:105], v[226:229], v[202:205], v[102:105]
	v_mfma_f32_16x16x32_bf16 v[98:101], v[230:233], v[198:201], v[98:101]
	v_mfma_f32_16x16x32_bf16 v[98:101], v[234:237], v[202:205], v[98:101]
	v_mfma_f32_16x16x32_bf16 v[86:89], v[222:225], v[206:209], v[86:89]
	v_mfma_f32_16x16x32_bf16 v[86:89], v[226:229], v[210:213], v[86:89]
	v_mfma_f32_16x16x32_bf16 v[82:85], v[230:233], v[206:209], v[82:85]
	v_mfma_f32_16x16x32_bf16 v[82:85], v[234:237], v[210:213], v[82:85]
	v_mfma_f32_16x16x32_bf16 v[70:73], v[222:225], v[214:217], v[70:73]
	v_mfma_f32_16x16x32_bf16 v[70:73], v[226:229], v[218:221], v[70:73]
	v_mfma_f32_16x16x32_bf16 v[66:69], v[230:233], v[214:217], v[66:69]
	v_mfma_f32_16x16x32_bf16 v[66:69], v[234:237], v[218:221], v[66:69]
	s_setprio 0
	s_mov_b32 m0, s95
	v_lshl_add_u64 v[238:239], v[242:243], 0, s[12:13]
	s_barrier
	ds_read_b128 v[190:193], v169 offset:49152
	ds_read_b128 v[194:197], v169 offset:50176
	ds_read_b128 v[198:201], v169 offset:51200
	ds_read_b128 v[202:205], v169 offset:52224
	ds_read_b128 v[206:209], v169 offset:53248
	ds_read_b128 v[210:213], v169 offset:54272
	ds_read_b128 v[214:217], v169 offset:55296
	ds_read_b128 v[218:221], v169 offset:56320
	global_load_lds_dwordx4 v[238:239], off
	v_lshl_add_u64 v[238:239], v[244:245], 0, s[12:13]
	s_mov_b32 m0, s96
	s_nop 0
	global_load_lds_dwordx4 v[238:239], off
	s_barrier
	s_waitcnt lgkmcnt(0)
	s_setprio 1
	s_waitcnt lgkmcnt(0)
	v_mfma_f32_16x16x32_bf16 v[62:65], v[142:145], v[190:193], v[62:65]
	v_mfma_f32_16x16x32_bf16 v[62:65], v[162:165], v[194:197], v[62:65]
	v_mfma_f32_16x16x32_bf16 v[58:61], v[182:185], v[190:193], v[58:61]
	v_mfma_f32_16x16x32_bf16 v[58:61], v[186:189], v[194:197], v[58:61]
	v_mfma_f32_16x16x32_bf16 v[46:49], v[142:145], v[198:201], v[46:49]
	v_mfma_f32_16x16x32_bf16 v[46:49], v[162:165], v[202:205], v[46:49]
	v_mfma_f32_16x16x32_bf16 v[42:45], v[182:185], v[198:201], v[42:45]
	v_mfma_f32_16x16x32_bf16 v[42:45], v[186:189], v[202:205], v[42:45]
	v_mfma_f32_16x16x32_bf16 v[30:33], v[142:145], v[206:209], v[30:33]
	v_mfma_f32_16x16x32_bf16 v[30:33], v[162:165], v[210:213], v[30:33]
	v_mfma_f32_16x16x32_bf16 v[26:29], v[182:185], v[206:209], v[26:29]
	v_mfma_f32_16x16x32_bf16 v[26:29], v[186:189], v[210:213], v[26:29]
	v_mfma_f32_16x16x32_bf16 v[14:17], v[142:145], v[214:217], v[14:17]
	v_mfma_f32_16x16x32_bf16 v[14:17], v[162:165], v[218:221], v[14:17]
	v_mfma_f32_16x16x32_bf16 v[10:13], v[182:185], v[214:217], v[10:13]
	v_mfma_f32_16x16x32_bf16 v[10:13], v[186:189], v[218:221], v[10:13]
	s_setprio 0
	s_barrier
	s_add_u32 s24, s48, 0x40080
	s_addc_u32 s25, s49, 0
	s_add_i32 s48, s60, s86
	v_lshl_add_u64 v[142:143], s[24:25], 0, v[134:135]
	s_mov_b32 m0, s48
	s_nop 0
	global_load_lds_dwordx4 v[142:143], off
	v_lshl_add_u64 v[142:143], s[24:25], 0, v[130:131]
	s_add_i32 m0, s48, 0x2000
	s_nop 0
	global_load_lds_dwordx4 v[142:143], off
	s_waitcnt vmcnt(6)
	s_barrier
	s_setprio 1
	v_mfma_f32_16x16x32_bf16 v[54:57], v[222:225], v[190:193], v[54:57]
	v_mfma_f32_16x16x32_bf16 v[54:57], v[226:229], v[194:197], v[54:57]
	v_mfma_f32_16x16x32_bf16 v[50:53], v[230:233], v[190:193], v[50:53]
	v_mfma_f32_16x16x32_bf16 v[50:53], v[234:237], v[194:197], v[50:53]
	v_mfma_f32_16x16x32_bf16 v[38:41], v[222:225], v[198:201], v[38:41]
	v_mfma_f32_16x16x32_bf16 v[38:41], v[226:229], v[202:205], v[38:41]
	v_mfma_f32_16x16x32_bf16 v[34:37], v[230:233], v[198:201], v[34:37]
	v_mfma_f32_16x16x32_bf16 v[34:37], v[234:237], v[202:205], v[34:37]
	v_mfma_f32_16x16x32_bf16 v[22:25], v[222:225], v[206:209], v[22:25]
	v_mfma_f32_16x16x32_bf16 v[22:25], v[226:229], v[210:213], v[22:25]
	v_mfma_f32_16x16x32_bf16 v[18:21], v[230:233], v[206:209], v[18:21]
	v_mfma_f32_16x16x32_bf16 v[18:21], v[234:237], v[210:213], v[18:21]
	v_mfma_f32_16x16x32_bf16 v[6:9], v[222:225], v[214:217], v[6:9]
	v_mfma_f32_16x16x32_bf16 v[6:9], v[226:229], v[218:221], v[6:9]
	v_mfma_f32_16x16x32_bf16 v[2:5], v[230:233], v[214:217], v[2:5]
	v_mfma_f32_16x16x32_bf16 v[2:5], v[234:237], v[218:221], v[2:5]
	s_setprio 0
	s_add_i32 s50, s50, 2
	s_add_u32 vcc_lo, vcc_lo, 0x100
	s_addc_u32 s35, s35, 0
	s_add_u32 s38, s38, 0x100
	s_addc_u32 s39, s39, 0
	s_cmp_gt_u32 s50, 13
	s_barrier
	s_cbranch_scc0 .LBB0_165
	s_and_b64 vcc, exec, s[40:41]
	s_cbranch_vccz .LBB0_168
	s_barrier

; #define PG8_STAGE(bufoff, gbase, voff) do { _Pragma("unroll") for (int _i = 0; _i < 2; ++_i) \
;         __builtin_amdgcn_global_load_lds((const unsigned*)((const char*)(gbase) + (voff)[_i]), (LAS unsigned*)(lds + (bufoff) + ldsw + _i * 8192), 16, 0, 0); } while (0)
; #define PG8_LDA(dst, b, h) do { _Pragma("unroll") for (int m = 0; m < 4; ++m) _Pragma("unroll") for (int k = 0; k < 2; ++k) dst[m][k] = *(const LAS bf16x8*)(lds + PG8_SA(b, h) + aoff + m * 2048 + k * 1024); } while (0)
; #define PG8_LDB(dst, b, h) do { _Pragma("unroll") for (int n = 0; n < 2; ++n) _Pragma("unroll") for (int k = 0; k < 2; ++k) dst[n][k] = *(const LAS bf16x8*)(lds + PG8_SB(b, h) + boff + n * 2048 + k * 1024); } while (0)
; #define PG8_MMA(ai, bj, At, Bt) do { __builtin_amdgcn_s_setprio(1); _Pragma("unroll") for (int m = 0; m < 4; ++m) _Pragma("unroll") for (int n = 0; n < 2; ++n) _Pragma("unroll") for (int k = 0; k < 2; ++k) \
;         acc[ai][bj][m][n] = __builtin_amdgcn_mfma_f32_16x16x32_bf16(Bt[n][k], At[m][k], acc[ai][bj][m][n], 0, 0, 0); __builtin_amdgcn_s_setprio(0); } while (0)
; #define PG8_WAIT_L(n) asm volatile("s_waitcnt lgkmcnt(" #n ")" ::: "memory")
; #define PG8_BAR __builtin_amdgcn_s_barrier()
; #define PG8_SCHED __builtin_amdgcn_sched_barrier(0)
; template <class Epi, class Sched>
; __device__ __forceinline__ void gemm_phase(LAS unsigned char* lds, const Gemm g, const Sched& S, const Epi& E) {
;     ...
;         for (int t = 0; t < nt; t += 2) {
;             const bool last = (t == nt - 2);
;             const char* a1 = cA + (size_t)(t + 1) * kstep;
;             const char* a2 = last ? nA : cA + (size_t)(t + 2) * kstep; const char* b2 = last ? nB : cB + (size_t)(t + 2) * kstep;
;             const char* a3 = a2 + kstep; const char* b3 = b2 + kstep;
;             PG8_LDB(B0, 0, 0); PG8_SCHED; PG8_LDA(At, 0, 0); PG8_STAGE(PG8_SA(1, 1), a1 + hstep, voffA);
;             PG8_WAIT_L(8); PG8_BAR; PG8_WAIT_L(0); PG8_MMA(0, 0, At, B0); PG8_BAR; PG8_SCHED;
;             PG8_LDB(B1, 0, 1); PG8_STAGE(PG8_SB(0, 0), b2, voffB);
;             PG8_BAR; PG8_WAIT_L(0); PG8_MMA(0, 1, At, B1); PG8_BAR;
;             PG8_LDA(At, 0, 1); PG8_STAGE(PG8_SA(0, 0), a2, voffA);
;             PG8_BAR; PG8_WAIT_L(0); PG8_MMA(1, 0, At, B0); PG8_BAR; PG8_SCHED;
.LBB0_416:
	s_add_u32 s24, s0, 0xfffc0080
	s_addc_u32 s25, s1, -1
	s_add_i32 s39, 0, 0x10000
	v_add_u32_e32 v142, s39, v144
	ds_read_b128 v[164:167], v142
	ds_read_b128 v[182:185], v142 offset:1024
	ds_read_b128 v[186:189], v142 offset:2048
	ds_read_b128 v[190:193], v142 offset:3072
	s_cmp_eq_u32 s38, 12
	s_cselect_b32 vcc_hi, s77, s25
	s_cselect_b32 vcc_lo, s76, s24
	s_cselect_b32 s37, s47, s50
	s_cselect_b32 s36, s61, s35
	v_lshl_add_u64 v[142:143], s[0:1], 0, v[140:141]
	s_add_i32 m0, s93, 0xc000
	ds_read_b128 v[194:197], v162
	ds_read_b128 v[198:201], v162 offset:1024
	ds_read_b128 v[202:205], v162 offset:2048
	ds_read_b128 v[206:209], v162 offset:3072
	ds_read_b128 v[210:213], v162 offset:4096
	ds_read_b128 v[214:217], v162 offset:5120
	ds_read_b128 v[218:221], v162 offset:6144
	ds_read_b128 v[222:225], v162 offset:7168
	global_load_lds_dwordx4 v[142:143], off
	v_lshl_add_u64 v[142:143], s[0:1], 0, v[138:139]
	s_add_i32 m0, s93, 0xe000
	s_nop 0
	global_load_lds_dwordx4 v[142:143], off
	s_waitcnt lgkmcnt(8)
	s_barrier
	s_waitcnt lgkmcnt(0)
	s_setprio 1
	s_waitcnt lgkmcnt(0)
	v_mfma_f32_16x16x32_bf16 v[126:129], v[164:167], v[194:197], v[126:129]
	v_mfma_f32_16x16x32_bf16 v[126:129], v[182:185], v[198:201], v[126:129]
	v_mfma_f32_16x16x32_bf16 v[122:125], v[186:189], v[194:197], v[122:125]
	v_mfma_f32_16x16x32_bf16 v[122:125], v[190:193], v[198:201], v[122:125]
	v_mfma_f32_16x16x32_bf16 v[118:121], v[164:167], v[202:205], v[118:121]
	v_mfma_f32_16x16x32_bf16 v[118:121], v[182:185], v[206:209], v[118:121]
	v_mfma_f32_16x16x32_bf16 v[110:113], v[186:189], v[202:205], v[110:113]
	v_mfma_f32_16x16x32_bf16 v[110:113], v[190:193], v[206:209], v[110:113]
	v_mfma_f32_16x16x32_bf16 v[102:105], v[164:167], v[210:213], v[102:105]
	v_mfma_f32_16x16x32_bf16 v[102:105], v[182:185], v[214:217], v[102:105]
	v_mfma_f32_16x16x32_bf16 v[94:97], v[186:189], v[210:213], v[94:97]
	v_mfma_f32_16x16x32_bf16 v[94:97], v[190:193], v[214:217], v[94:97]
	v_mfma_f32_16x16x32_bf16 v[86:89], v[164:167], v[218:221], v[86:89]
	v_mfma_f32_16x16x32_bf16 v[86:89], v[182:185], v[222:225], v[86:89]
	v_mfma_f32_16x16x32_bf16 v[78:81], v[186:189], v[218:221], v[78:81]
	v_mfma_f32_16x16x32_bf16 v[78:81], v[190:193], v[222:225], v[78:81]
	s_setprio 0
	s_barrier
	s_add_i32 s51, 0, 0x14000
	v_add_u32_e32 v142, s51, v144
	s_add_i32 s24, s39, s86
	ds_read_b128 v[226:229], v142
	ds_read_b128 v[230:233], v142 offset:1024
	ds_read_b128 v[234:237], v142 offset:2048
	ds_read_b128 v[238:241], v142 offset:3072
	v_lshl_add_u64 v[142:143], s[36:37], 0, v[134:135]
	s_mov_b32 m0, s24
	v_lshl_add_u64 v[168:169], s[36:37], 0, v[130:131]
	global_load_lds_dwordx4 v[142:143], off
	s_add_i32 m0, s24, 0x2000
	s_nop 0
	global_load_lds_dwordx4 v[168:169], off
	s_barrier
	s_waitcnt lgkmcnt(0)
	s_setprio 1
	s_waitcnt lgkmcnt(0)
	v_mfma_f32_16x16x32_bf16 v[114:117], v[226:229], v[194:197], v[114:117]
	v_mfma_f32_16x16x32_bf16 v[114:117], v[230:233], v[198:201], v[114:117]
	v_mfma_f32_16x16x32_bf16 v[106:109], v[234:237], v[194:197], v[106:109]
	v_mfma_f32_16x16x32_bf16 v[106:109], v[238:241], v[198:201], v[106:109]
	v_mfma_f32_16x16x32_bf16 v[98:101], v[226:229], v[202:205], v[98:101]
	v_mfma_f32_16x16x32_bf16 v[98:101], v[230:233], v[206:209], v[98:101]
	v_mfma_f32_16x16x32_bf16 v[90:93], v[234:237], v[202:205], v[90:93]
	v_mfma_f32_16x16x32_bf16 v[90:93], v[238:241], v[206:209], v[90:93]
	v_mfma_f32_16x16x32_bf16 v[82:85], v[226:229], v[210:213], v[82:85]
	v_mfma_f32_16x16x32_bf16 v[82:85], v[230:233], v[214:217], v[82:85]
	v_mfma_f32_16x16x32_bf16 v[74:77], v[234:237], v[210:213], v[74:77]
	v_mfma_f32_16x16x32_bf16 v[74:77], v[238:241], v[214:217], v[74:77]
	v_mfma_f32_16x16x32_bf16 v[70:73], v[226:229], v[218:221], v[70:73]
	v_mfma_f32_16x16x32_bf16 v[70:73], v[230:233], v[222:225], v[70:73]
	v_mfma_f32_16x16x32_bf16 v[66:69], v[234:237], v[218:221], v[66:69]
	v_mfma_f32_16x16x32_bf16 v[66:69], v[238:241], v[222:225], v[66:69]
	s_setprio 0
	s_mov_b32 m0, s93
	v_lshl_add_u64 v[242:243], vcc, 0, v[136:137]
	s_barrier
	ds_read_b128 v[194:197], v162 offset:16384
	ds_read_b128 v[198:201], v162 offset:17408
	ds_read_b128 v[202:205], v162 offset:18432
	ds_read_b128 v[206:209], v162 offset:19456
	ds_read_b128 v[210:213], v162 offset:20480
	ds_read_b128 v[214:217], v162 offset:21504
	ds_read_b128 v[218:221], v162 offset:22528
	ds_read_b128 v[222:225], v162 offset:23552
	global_load_lds_dwordx4 v[242:243], off
	v_lshl_add_u64 v[244:245], vcc, 0, v[132:133]
	s_mov_b32 m0, s94
	s_nop 0
	global_load_lds_dwordx4 v[244:245], off
	s_barrier
	s_waitcnt lgkmcnt(0)
	s_setprio 1
	s_waitcnt lgkmcnt(0)
	v_mfma_f32_16x16x32_bf16 v[62:65], v[164:167], v[194:197], v[62:65]
	v_mfma_f32_16x16x32_bf16 v[62:65], v[182:185], v[198:201], v[62:65]
	v_mfma_f32_16x16x32_bf16 v[58:61], v[186:189], v[194:197], v[58:61]
	v_mfma_f32_16x16x32_bf16 v[58:61], v[190:193], v[198:201], v[58:61]
	v_mfma_f32_16x16x32_bf16 v[54:57], v[164:167], v[202:205], v[54:57]
	v_mfma_f32_16x16x32_bf16 v[54:57], v[182:185], v[206:209], v[54:57]
	v_mfma_f32_16x16x32_bf16 v[46:49], v[186:189], v[202:205], v[46:49]
	v_mfma_f32_16x16x32_bf16 v[46:49], v[190:193], v[206:209], v[46:49]
	v_mfma_f32_16x16x32_bf16 v[38:41], v[164:167], v[210:213], v[38:41]
	v_mfma_f32_16x16x32_bf16 v[38:41], v[182:185], v[214:217], v[38:41]
	v_mfma_f32_16x16x32_bf16 v[30:33], v[186:189], v[210:213], v[30:33]
	v_mfma_f32_16x16x32_bf16 v[30:33], v[190:193], v[214:217], v[30:33]
	v_mfma_f32_16x16x32_bf16 v[22:25], v[164:167], v[218:221], v[22:25]
	v_mfma_f32_16x16x32_bf16 v[22:25], v[182:185], v[222:225], v[22:25]
	v_mfma_f32_16x16x32_bf16 v[14:17], v[186:189], v[218:221], v[14:17]
	v_mfma_f32_16x16x32_bf16 v[14:17], v[190:193], v[222:225], v[14:17]
	s_setprio 0
	s_barrier
; #define PG8_STAGE(bufoff, gbase, voff) do { _Pragma("unroll") for (int _i = 0; _i < 2; ++_i) \
;         __builtin_amdgcn_global_load_lds((const unsigned*)((const char*)(gbase) + (voff)[_i]), (LAS unsigned*)(lds + (bufoff) + ldsw + _i * 8192), 16, 0, 0); } while (0)
; #define PG8_LDA(dst, b, h) do { _Pragma("unroll") for (int m = 0; m < 4; ++m) _Pragma("unroll") for (int k = 0; k < 2; ++k) dst[m][k] = *(const LAS bf16x8*)(lds + PG8_SA(b, h) + aoff + m * 2048 + k * 1024); } while (0)
; #define PG8_LDB(dst, b, h) do { _Pragma("unroll") for (int n = 0; n < 2; ++n) _Pragma("unroll") for (int k = 0; k < 2; ++k) dst[n][k] = *(const LAS bf16x8*)(lds + PG8_SB(b, h) + boff + n * 2048 + k * 1024); } while (0)
; #define PG8_MMA(ai, bj, At, Bt) do { __builtin_amdgcn_s_setprio(1); _Pragma("unroll") for (int m = 0; m < 4; ++m) _Pragma("unroll") for (int n = 0; n < 2; ++n) _Pragma("unroll") for (int k = 0; k < 2; ++k) \
;         acc[ai][bj][m][n] = __builtin_amdgcn_mfma_f32_16x16x32_bf16(Bt[n][k], At[m][k], acc[ai][bj][m][n], 0, 0, 0); __builtin_amdgcn_s_setprio(0); } while (0)
; #define PG8_WAIT_V(n) asm volatile("s_waitcnt vmcnt(" #n ")" ::: "memory")
; #define PG8_WAIT_L(n) asm volatile("s_waitcnt lgkmcnt(" #n ")" ::: "memory")
; #define PG8_BAR __builtin_amdgcn_s_barrier()
; #define PG8_SCHED __builtin_amdgcn_sched_barrier(0)
; template <class Epi, class Sched>
; __device__ __forceinline__ void gemm_phase(LAS unsigned char* lds, const Gemm g, const Sched& S, const Epi& E) {
;     ...
;             PG8_STAGE(PG8_SB(0, 1), b2 + hstep, voffB);
;             PG8_WAIT_V(6); PG8_BAR; PG8_MMA(1, 1, At, B1); PG8_BAR;
;             PG8_LDB(B0, 1, 0); PG8_SCHED; PG8_LDA(At, 1, 0); PG8_STAGE(PG8_SA(0, 1), a2 + hstep, voffA);
;             PG8_WAIT_L(8); PG8_BAR; PG8_WAIT_L(0); PG8_MMA(0, 0, At, B0); PG8_BAR; PG8_SCHED;
;             PG8_LDB(B1, 1, 1); PG8_STAGE(PG8_SB(1, 0), b3, voffB);
;             PG8_BAR; PG8_WAIT_L(0); PG8_MMA(0, 1, At, B1); PG8_BAR;
	s_add_u32 s24, s36, 0x40000
	s_addc_u32 s25, s37, 0
	s_add_i32 s39, s51, s86
	v_lshl_add_u64 v[164:165], s[24:25], 0, v[134:135]
	s_mov_b32 m0, s39
	s_nop 0
	global_load_lds_dwordx4 v[164:165], off
	v_lshl_add_u64 v[164:165], s[24:25], 0, v[130:131]
	s_add_i32 m0, s39, 0x2000
	s_nop 0
	global_load_lds_dwordx4 v[164:165], off
	s_waitcnt vmcnt(6)
	s_barrier
	s_setprio 1
	v_mfma_f32_16x16x32_bf16 v[50:53], v[226:229], v[194:197], v[50:53]
	v_mfma_f32_16x16x32_bf16 v[50:53], v[230:233], v[198:201], v[50:53]
	v_mfma_f32_16x16x32_bf16 v[42:45], v[234:237], v[194:197], v[42:45]
	v_mfma_f32_16x16x32_bf16 v[42:45], v[238:241], v[198:201], v[42:45]
	v_mfma_f32_16x16x32_bf16 v[34:37], v[226:229], v[202:205], v[34:37]
	v_mfma_f32_16x16x32_bf16 v[34:37], v[230:233], v[206:209], v[34:37]
	v_mfma_f32_16x16x32_bf16 v[26:29], v[234:237], v[202:205], v[26:29]
	v_mfma_f32_16x16x32_bf16 v[26:29], v[238:241], v[206:209], v[26:29]
	v_mfma_f32_16x16x32_bf16 v[18:21], v[226:229], v[210:213], v[18:21]
	v_mfma_f32_16x16x32_bf16 v[18:21], v[230:233], v[214:217], v[18:21]
	v_mfma_f32_16x16x32_bf16 v[10:13], v[234:237], v[210:213], v[10:13]
	v_mfma_f32_16x16x32_bf16 v[10:13], v[238:241], v[214:217], v[10:13]
	v_mfma_f32_16x16x32_bf16 v[6:9], v[226:229], v[218:221], v[6:9]
	v_mfma_f32_16x16x32_bf16 v[6:9], v[230:233], v[222:225], v[6:9]
	v_mfma_f32_16x16x32_bf16 v[2:5], v[234:237], v[218:221], v[2:5]
	v_mfma_f32_16x16x32_bf16 v[2:5], v[238:241], v[222:225], v[2:5]
	s_setprio 0
	s_add_i32 s39, 0, 0x18000
	v_add_u32_e32 v163, s39, v144
	s_barrier
	ds_read_b128 v[164:167], v163
	ds_read_b128 v[182:185], v163 offset:1024
	ds_read_b128 v[186:189], v163 offset:2048
	ds_read_b128 v[190:193], v163 offset:3072
	s_add_u32 s24, vcc_lo, 0x40000
	s_addc_u32 s25, vcc_hi, 0
	s_mov_b32 m0, s95
	v_lshl_add_u64 v[226:227], s[24:25], 0, v[136:137]
	ds_read_b128 v[194:197], v162 offset:32768
	ds_read_b128 v[198:201], v162 offset:33792
	ds_read_b128 v[202:205], v162 offset:34816
	ds_read_b128 v[206:209], v162 offset:35840
	ds_read_b128 v[210:213], v162 offset:36864
	ds_read_b128 v[214:217], v162 offset:37888
	ds_read_b128 v[218:221], v162 offset:38912
	ds_read_b128 v[222:225], v162 offset:39936
	global_load_lds_dwordx4 v[226:227], off
	v_lshl_add_u64 v[226:227], s[24:25], 0, v[132:133]
	s_mov_b32 m0, s96
	s_nop 0
	global_load_lds_dwordx4 v[226:227], off
	s_waitcnt lgkmcnt(8)
	s_barrier
	s_waitcnt lgkmcnt(0)
	s_setprio 1
	s_waitcnt lgkmcnt(0)
	v_mfma_f32_16x16x32_bf16 v[126:129], v[164:167], v[194:197], v[126:129]
	v_mfma_f32_16x16x32_bf16 v[126:129], v[182:185], v[198:201], v[126:129]
	v_mfma_f32_16x16x32_bf16 v[122:125], v[186:189], v[194:197], v[122:125]
	v_mfma_f32_16x16x32_bf16 v[122:125], v[190:193], v[198:201], v[122:125]
	v_mfma_f32_16x16x32_bf16 v[118:121], v[164:167], v[202:205], v[118:121]
	v_mfma_f32_16x16x32_bf16 v[118:121], v[182:185], v[206:209], v[118:121]
	v_mfma_f32_16x16x32_bf16 v[110:113], v[186:189], v[202:205], v[110:113]
	v_mfma_f32_16x16x32_bf16 v[110:113], v[190:193], v[206:209], v[110:113]
	v_mfma_f32_16x16x32_bf16 v[102:105], v[164:167], v[210:213], v[102:105]
	v_mfma_f32_16x16x32_bf16 v[102:105], v[182:185], v[214:217], v[102:105]
	v_mfma_f32_16x16x32_bf16 v[94:97], v[186:189], v[210:213], v[94:97]
	v_mfma_f32_16x16x32_bf16 v[94:97], v[190:193], v[214:217], v[94:97]
	v_mfma_f32_16x16x32_bf16 v[86:89], v[164:167], v[218:221], v[86:89]
	v_mfma_f32_16x16x32_bf16 v[86:89], v[182:185], v[222:225], v[86:89]
	v_mfma_f32_16x16x32_bf16 v[78:81], v[186:189], v[218:221], v[78:81]
	v_mfma_f32_16x16x32_bf16 v[78:81], v[190:193], v[222:225], v[78:81]
	s_setprio 0
	s_barrier
	s_add_i32 s51, 0, 0x1c000
	s_add_i32 s24, s39, s86
	v_add_u32_e32 v163, s51, v144
	v_lshl_add_u64 v[142:143], v[142:143], 0, s[12:13]
	s_mov_b32 m0, s24
	ds_read_b128 v[226:229], v163
	ds_read_b128 v[230:233], v163 offset:1024
	ds_read_b128 v[234:237], v163 offset:2048
	ds_read_b128 v[238:241], v163 offset:3072
	global_load_lds_dwordx4 v[142:143], off
	v_lshl_add_u64 v[142:143], v[168:169], 0, s[12:13]
	s_add_i32 m0, s24, 0x2000
	s_nop 0
	global_load_lds_dwordx4 v[142:143], off
	s_barrier
; #define PG8_STAGE(bufoff, gbase, voff) do { _Pragma("unroll") for (int _i = 0; _i < 2; ++_i) \
;         __builtin_amdgcn_global_load_lds((const unsigned*)((const char*)(gbase) + (voff)[_i]), (LAS unsigned*)(lds + (bufoff) + ldsw + _i * 8192), 16, 0, 0); } while (0)
; #define PG8_LDA(dst, b, h) do { _Pragma("unroll") for (int m = 0; m < 4; ++m) _Pragma("unroll") for (int k = 0; k < 2; ++k) dst[m][k] = *(const LAS bf16x8*)(lds + PG8_SA(b, h) + aoff + m * 2048 + k * 1024); } while (0)
; #define PG8_MMA(ai, bj, At, Bt) do { __builtin_amdgcn_s_setprio(1); _Pragma("unroll") for (int m = 0; m < 4; ++m) _Pragma("unroll") for (int n = 0; n < 2; ++n) _Pragma("unroll") for (int k = 0; k < 2; ++k) \
;         acc[ai][bj][m][n] = __builtin_amdgcn_mfma_f32_16x16x32_bf16(Bt[n][k], At[m][k], acc[ai][bj][m][n], 0, 0, 0); __builtin_amdgcn_s_setprio(0); } while (0)
; #define PG8_WAIT_V(n) asm volatile("s_waitcnt vmcnt(" #n ")" ::: "memory")
; #define PG8_WAIT_L(n) asm volatile("s_waitcnt lgkmcnt(" #n ")" ::: "memory")
; #define PG8_BAR __builtin_amdgcn_s_barrier()
; #define PG8_SCHED __builtin_amdgcn_sched_barrier(0)
; template <class Epi, class Sched>
; __device__ __forceinline__ void gemm_phase(LAS unsigned char* lds, const Gemm g, const Sched& S, const Epi& E) {
;     ...
;             PG8_LDA(At, 1, 1); PG8_STAGE(PG8_SA(1, 0), a3, voffA);
;             PG8_BAR; PG8_WAIT_L(0); PG8_MMA(1, 0, At, B0); PG8_BAR; PG8_SCHED;
;             PG8_STAGE(PG8_SB(1, 1), b3 + hstep, voffB);
;             PG8_WAIT_V(6); PG8_BAR; PG8_MMA(1, 1, At, B1); PG8_BAR;
;         }
;         if (wr == 0) PG8_BAR;
	s_waitcnt lgkmcnt(0)
	s_setprio 1
	s_waitcnt lgkmcnt(0)
	v_mfma_f32_16x16x32_bf16 v[114:117], v[226:229], v[194:197], v[114:117]
	v_mfma_f32_16x16x32_bf16 v[114:117], v[230:233], v[198:201], v[114:117]
	v_mfma_f32_16x16x32_bf16 v[106:109], v[234:237], v[194:197], v[106:109]
	v_mfma_f32_16x16x32_bf16 v[106:109], v[238:241], v[198:201], v[106:109]
	v_mfma_f32_16x16x32_bf16 v[98:101], v[226:229], v[202:205], v[98:101]
	v_mfma_f32_16x16x32_bf16 v[98:101], v[230:233], v[206:209], v[98:101]
	v_mfma_f32_16x16x32_bf16 v[90:93], v[234:237], v[202:205], v[90:93]
	v_mfma_f32_16x16x32_bf16 v[90:93], v[238:241], v[206:209], v[90:93]
	v_mfma_f32_16x16x32_bf16 v[82:85], v[226:229], v[210:213], v[82:85]
	v_mfma_f32_16x16x32_bf16 v[82:85], v[230:233], v[214:217], v[82:85]
	v_mfma_f32_16x16x32_bf16 v[74:77], v[234:237], v[210:213], v[74:77]
	v_mfma_f32_16x16x32_bf16 v[74:77], v[238:241], v[214:217], v[74:77]
	v_mfma_f32_16x16x32_bf16 v[70:73], v[226:229], v[218:221], v[70:73]
	v_mfma_f32_16x16x32_bf16 v[70:73], v[230:233], v[222:225], v[70:73]
	v_mfma_f32_16x16x32_bf16 v[66:69], v[234:237], v[218:221], v[66:69]
	v_mfma_f32_16x16x32_bf16 v[66:69], v[238:241], v[222:225], v[66:69]
	s_setprio 0
	s_mov_b32 m0, s97
	v_lshl_add_u64 v[142:143], v[242:243], 0, s[12:13]
	s_barrier
	ds_read_b128 v[194:197], v162 offset:49152
	ds_read_b128 v[198:201], v162 offset:50176
	ds_read_b128 v[202:205], v162 offset:51200
	ds_read_b128 v[206:209], v162 offset:52224
	ds_read_b128 v[210:213], v162 offset:53248
	ds_read_b128 v[214:217], v162 offset:54272
	ds_read_b128 v[218:221], v162 offset:55296
	ds_read_b128 v[222:225], v162 offset:56320
	global_load_lds_dwordx4 v[142:143], off
	v_lshl_add_u64 v[142:143], v[244:245], 0, s[12:13]
	s_mov_b32 m0, s98
	s_nop 0
	global_load_lds_dwordx4 v[142:143], off
	s_barrier
	s_waitcnt lgkmcnt(0)
	s_setprio 1
	s_waitcnt lgkmcnt(0)
	v_mfma_f32_16x16x32_bf16 v[62:65], v[164:167], v[194:197], v[62:65]
	v_mfma_f32_16x16x32_bf16 v[62:65], v[182:185], v[198:201], v[62:65]
	v_mfma_f32_16x16x32_bf16 v[58:61], v[186:189], v[194:197], v[58:61]
	v_mfma_f32_16x16x32_bf16 v[58:61], v[190:193], v[198:201], v[58:61]
	v_mfma_f32_16x16x32_bf16 v[54:57], v[164:167], v[202:205], v[54:57]
	v_mfma_f32_16x16x32_bf16 v[54:57], v[182:185], v[206:209], v[54:57]
	v_mfma_f32_16x16x32_bf16 v[46:49], v[186:189], v[202:205], v[46:49]
	v_mfma_f32_16x16x32_bf16 v[46:49], v[190:193], v[206:209], v[46:49]
	v_mfma_f32_16x16x32_bf16 v[38:41], v[164:167], v[210:213], v[38:41]
	v_mfma_f32_16x16x32_bf16 v[38:41], v[182:185], v[214:217], v[38:41]
	v_mfma_f32_16x16x32_bf16 v[30:33], v[186:189], v[210:213], v[30:33]
	v_mfma_f32_16x16x32_bf16 v[30:33], v[190:193], v[214:217], v[30:33]
	v_mfma_f32_16x16x32_bf16 v[22:25], v[164:167], v[218:221], v[22:25]
	v_mfma_f32_16x16x32_bf16 v[22:25], v[182:185], v[222:225], v[22:25]
	v_mfma_f32_16x16x32_bf16 v[14:17], v[186:189], v[218:221], v[14:17]
	v_mfma_f32_16x16x32_bf16 v[14:17], v[190:193], v[222:225], v[14:17]
	s_setprio 0
	s_barrier
	s_add_u32 s24, s36, 0x40080
	s_addc_u32 s25, s37, 0
	s_add_i32 s36, s51, s86
	v_lshl_add_u64 v[142:143], s[24:25], 0, v[134:135]
	s_mov_b32 m0, s36
	s_nop 0
	global_load_lds_dwordx4 v[142:143], off
	v_lshl_add_u64 v[142:143], s[24:25], 0, v[130:131]
	s_add_i32 m0, s36, 0x2000
	s_nop 0
	global_load_lds_dwordx4 v[142:143], off
	s_waitcnt vmcnt(6)
	s_barrier
	s_setprio 1
	v_mfma_f32_16x16x32_bf16 v[50:53], v[226:229], v[194:197], v[50:53]
	v_mfma_f32_16x16x32_bf16 v[50:53], v[230:233], v[198:201], v[50:53]
	v_mfma_f32_16x16x32_bf16 v[42:45], v[234:237], v[194:197], v[42:45]
	v_mfma_f32_16x16x32_bf16 v[42:45], v[238:241], v[198:201], v[42:45]
	v_mfma_f32_16x16x32_bf16 v[34:37], v[226:229], v[202:205], v[34:37]
	v_mfma_f32_16x16x32_bf16 v[34:37], v[230:233], v[206:209], v[34:37]
	v_mfma_f32_16x16x32_bf16 v[26:29], v[234:237], v[202:205], v[26:29]
	v_mfma_f32_16x16x32_bf16 v[26:29], v[238:241], v[206:209], v[26:29]
	v_mfma_f32_16x16x32_bf16 v[18:21], v[226:229], v[210:213], v[18:21]
	v_mfma_f32_16x16x32_bf16 v[18:21], v[230:233], v[214:217], v[18:21]
	v_mfma_f32_16x16x32_bf16 v[10:13], v[234:237], v[210:213], v[10:13]
	v_mfma_f32_16x16x32_bf16 v[10:13], v[238:241], v[214:217], v[10:13]
	v_mfma_f32_16x16x32_bf16 v[6:9], v[226:229], v[218:221], v[6:9]
	v_mfma_f32_16x16x32_bf16 v[6:9], v[230:233], v[222:225], v[6:9]
	v_mfma_f32_16x16x32_bf16 v[2:5], v[234:237], v[218:221], v[2:5]
	v_mfma_f32_16x16x32_bf16 v[2:5], v[238:241], v[222:225], v[2:5]
	s_setprio 0
	s_add_i32 s38, s38, 2
	s_add_u32 s35, s35, 0x100
	s_addc_u32 s50, s50, 0
	s_add_u32 s0, s0, 0x100
	s_addc_u32 s1, s1, 0
	s_cmp_gt_u32 s38, 13
	s_barrier
	s_cbranch_scc0 .LBB0_416
	s_and_b64 vcc, exec, s[44:45]
	s_cbranch_vccz .LBB0_419
	s_barrier

; #define PG8_STAGE(bufoff, gbase, voff) do { _Pragma("unroll") for (int _i = 0; _i < 2; ++_i) \
;         __builtin_amdgcn_global_load_lds((const unsigned*)((const char*)(gbase) + (voff)[_i]), (LAS unsigned*)(lds + (bufoff) + ldsw + _i * 8192), 16, 0, 0); } while (0)
; #define PG8_LDA(dst, b, h) do { _Pragma("unroll") for (int m = 0; m < 4; ++m) _Pragma("unroll") for (int k = 0; k < 2; ++k) dst[m][k] = *(const LAS bf16x8*)(lds + PG8_SA(b, h) + aoff + m * 2048 + k * 1024); } while (0)
; #define PG8_LDB(dst, b, h) do { _Pragma("unroll") for (int n = 0; n < 2; ++n) _Pragma("unroll") for (int k = 0; k < 2; ++k) dst[n][k] = *(const LAS bf16x8*)(lds + PG8_SB(b, h) + boff + n * 2048 + k * 1024); } while (0)
; #define PG8_MMA(ai, bj, At, Bt) do { __builtin_amdgcn_s_setprio(1); _Pragma("unroll") for (int m = 0; m < 4; ++m) _Pragma("unroll") for (int n = 0; n < 2; ++n) _Pragma("unroll") for (int k = 0; k < 2; ++k) \
;         acc[ai][bj][m][n] = __builtin_amdgcn_mfma_f32_16x16x32_bf16(Bt[n][k], At[m][k], acc[ai][bj][m][n], 0, 0, 0); __builtin_amdgcn_s_setprio(0); } while (0)
; #define PG8_WAIT_L(n) asm volatile("s_waitcnt lgkmcnt(" #n ")" ::: "memory")
; #define PG8_BAR __builtin_amdgcn_s_barrier()
; #define PG8_SCHED __builtin_amdgcn_sched_barrier(0)
; template <class Epi, class Sched>
; __device__ __forceinline__ void gemm_phase(LAS unsigned char* lds, const Gemm g, const Sched& S, const Epi& E) {
;     ...
;         for (int t = 0; t < nt; t += 2) {
;             const bool last = (t == nt - 2);
;             const char* a1 = cA + (size_t)(t + 1) * kstep;
;             const char* a2 = last ? nA : cA + (size_t)(t + 2) * kstep; const char* b2 = last ? nB : cB + (size_t)(t + 2) * kstep;
;             const char* a3 = a2 + kstep; const char* b3 = b2 + kstep;
;             PG8_LDB(B0, 0, 0); PG8_SCHED; PG8_LDA(At, 0, 0); PG8_STAGE(PG8_SA(1, 1), a1 + hstep, voffA);
;             PG8_WAIT_L(8); PG8_BAR; PG8_WAIT_L(0); PG8_MMA(0, 0, At, B0); PG8_BAR; PG8_SCHED;
;             PG8_LDB(B1, 0, 1); PG8_STAGE(PG8_SB(0, 0), b2, voffB);
;             PG8_BAR; PG8_WAIT_L(0); PG8_MMA(0, 1, At, B1); PG8_BAR;
;             PG8_LDA(At, 0, 1); PG8_STAGE(PG8_SA(0, 0), a2, voffA);
;             PG8_BAR; PG8_WAIT_L(0); PG8_MMA(1, 0, At, B0); PG8_BAR; PG8_SCHED;
.LBB0_557:
	s_add_u32 s24, s0, 0xfffc0080
	s_addc_u32 s25, s1, -1
	s_add_i32 s39, 0, 0x10000
	v_add_u32_e32 v162, s39, v164
	ds_read_b128 v[142:145], v162
	ds_read_b128 v[182:185], v162 offset:1024
	ds_read_b128 v[186:189], v162 offset:2048
	ds_read_b128 v[190:193], v162 offset:3072
	s_cmp_eq_u32 s38, 12
	s_cselect_b32 vcc_hi, s77, s25
	s_cselect_b32 vcc_lo, s76, s24
	s_cselect_b32 s49, s45, s50
	s_cselect_b32 s48, s47, s35
	v_lshl_add_u64 v[162:163], s[0:1], 0, v[140:141]
	s_add_i32 m0, s95, 0xc000
	ds_read_b128 v[194:197], v166
	ds_read_b128 v[198:201], v166 offset:1024
	ds_read_b128 v[202:205], v166 offset:2048
	ds_read_b128 v[206:209], v166 offset:3072
	ds_read_b128 v[210:213], v166 offset:4096
	ds_read_b128 v[214:217], v166 offset:5120
	ds_read_b128 v[218:221], v166 offset:6144
	ds_read_b128 v[222:225], v166 offset:7168
	global_load_lds_dwordx4 v[162:163], off
	v_lshl_add_u64 v[162:163], s[0:1], 0, v[138:139]
	s_add_i32 m0, s95, 0xe000
	s_nop 0
	global_load_lds_dwordx4 v[162:163], off
	s_waitcnt lgkmcnt(8)
	s_barrier
	s_waitcnt lgkmcnt(0)
	s_setprio 1
	s_waitcnt lgkmcnt(0)
	v_mfma_f32_16x16x32_bf16 v[126:129], v[142:145], v[194:197], v[126:129]
	v_mfma_f32_16x16x32_bf16 v[126:129], v[182:185], v[198:201], v[126:129]
	v_mfma_f32_16x16x32_bf16 v[122:125], v[186:189], v[194:197], v[122:125]
	v_mfma_f32_16x16x32_bf16 v[122:125], v[190:193], v[198:201], v[122:125]
	v_mfma_f32_16x16x32_bf16 v[110:113], v[142:145], v[202:205], v[110:113]
	v_mfma_f32_16x16x32_bf16 v[110:113], v[182:185], v[206:209], v[110:113]
	v_mfma_f32_16x16x32_bf16 v[106:109], v[186:189], v[202:205], v[106:109]
	v_mfma_f32_16x16x32_bf16 v[106:109], v[190:193], v[206:209], v[106:109]
	v_mfma_f32_16x16x32_bf16 v[94:97], v[142:145], v[210:213], v[94:97]
	v_mfma_f32_16x16x32_bf16 v[94:97], v[182:185], v[214:217], v[94:97]
	v_mfma_f32_16x16x32_bf16 v[90:93], v[186:189], v[210:213], v[90:93]
	v_mfma_f32_16x16x32_bf16 v[90:93], v[190:193], v[214:217], v[90:93]
	v_mfma_f32_16x16x32_bf16 v[78:81], v[142:145], v[218:221], v[78:81]
	v_mfma_f32_16x16x32_bf16 v[78:81], v[182:185], v[222:225], v[78:81]
	v_mfma_f32_16x16x32_bf16 v[74:77], v[186:189], v[218:221], v[74:77]
	v_mfma_f32_16x16x32_bf16 v[74:77], v[190:193], v[222:225], v[74:77]
	s_setprio 0
	s_barrier
	s_add_i32 s51, 0, 0x14000
	v_add_u32_e32 v162, s51, v164
	s_add_i32 s24, s39, s94
	ds_read_b128 v[226:229], v162
	ds_read_b128 v[230:233], v162 offset:1024
	ds_read_b128 v[234:237], v162 offset:2048
	ds_read_b128 v[238:241], v162 offset:3072
	v_lshl_add_u64 v[162:163], s[48:49], 0, v[134:135]
	s_mov_b32 m0, s24
	v_lshl_add_u64 v[168:169], s[48:49], 0, v[130:131]
	global_load_lds_dwordx4 v[162:163], off
	s_add_i32 m0, s24, 0x2000
	s_nop 0
	global_load_lds_dwordx4 v[168:169], off
	s_barrier
	s_waitcnt lgkmcnt(0)
	s_setprio 1
	s_waitcnt lgkmcnt(0)
	v_mfma_f32_16x16x32_bf16 v[118:121], v[226:229], v[194:197], v[118:121]
	v_mfma_f32_16x16x32_bf16 v[118:121], v[230:233], v[198:201], v[118:121]
	v_mfma_f32_16x16x32_bf16 v[114:117], v[234:237], v[194:197], v[114:117]
	v_mfma_f32_16x16x32_bf16 v[114:117], v[238:241], v[198:201], v[114:117]
	v_mfma_f32_16x16x32_bf16 v[102:105], v[226:229], v[202:205], v[102:105]
	v_mfma_f32_16x16x32_bf16 v[102:105], v[230:233], v[206:209], v[102:105]
	v_mfma_f32_16x16x32_bf16 v[98:101], v[234:237], v[202:205], v[98:101]
	v_mfma_f32_16x16x32_bf16 v[98:101], v[238:241], v[206:209], v[98:101]
	v_mfma_f32_16x16x32_bf16 v[86:89], v[226:229], v[210:213], v[86:89]
	v_mfma_f32_16x16x32_bf16 v[86:89], v[230:233], v[214:217], v[86:89]
	v_mfma_f32_16x16x32_bf16 v[82:85], v[234:237], v[210:213], v[82:85]
	v_mfma_f32_16x16x32_bf16 v[82:85], v[238:241], v[214:217], v[82:85]
	v_mfma_f32_16x16x32_bf16 v[70:73], v[226:229], v[218:221], v[70:73]
	v_mfma_f32_16x16x32_bf16 v[70:73], v[230:233], v[222:225], v[70:73]
	v_mfma_f32_16x16x32_bf16 v[66:69], v[234:237], v[218:221], v[66:69]
	v_mfma_f32_16x16x32_bf16 v[66:69], v[238:241], v[222:225], v[66:69]
	s_setprio 0
	s_mov_b32 m0, s95
	v_lshl_add_u64 v[242:243], vcc, 0, v[136:137]
	s_barrier
	ds_read_b128 v[194:197], v166 offset:16384
	ds_read_b128 v[198:201], v166 offset:17408
	ds_read_b128 v[202:205], v166 offset:18432
	ds_read_b128 v[206:209], v166 offset:19456
	ds_read_b128 v[210:213], v166 offset:20480
	ds_read_b128 v[214:217], v166 offset:21504
	ds_read_b128 v[218:221], v166 offset:22528
	ds_read_b128 v[222:225], v166 offset:23552
	global_load_lds_dwordx4 v[242:243], off
	v_lshl_add_u64 v[244:245], vcc, 0, v[132:133]
	s_mov_b32 m0, s96
	s_nop 0
	global_load_lds_dwordx4 v[244:245], off
	s_barrier
	s_waitcnt lgkmcnt(0)
	s_setprio 1
	s_waitcnt lgkmcnt(0)
	v_mfma_f32_16x16x32_bf16 v[62:65], v[142:145], v[194:197], v[62:65]
	v_mfma_f32_16x16x32_bf16 v[62:65], v[182:185], v[198:201], v[62:65]
	v_mfma_f32_16x16x32_bf16 v[58:61], v[186:189], v[194:197], v[58:61]
	v_mfma_f32_16x16x32_bf16 v[58:61], v[190:193], v[198:201], v[58:61]
	v_mfma_f32_16x16x32_bf16 v[46:49], v[142:145], v[202:205], v[46:49]
	v_mfma_f32_16x16x32_bf16 v[46:49], v[182:185], v[206:209], v[46:49]
	v_mfma_f32_16x16x32_bf16 v[42:45], v[186:189], v[202:205], v[42:45]
	v_mfma_f32_16x16x32_bf16 v[42:45], v[190:193], v[206:209], v[42:45]
	v_mfma_f32_16x16x32_bf16 v[30:33], v[142:145], v[210:213], v[30:33]
	v_mfma_f32_16x16x32_bf16 v[30:33], v[182:185], v[214:217], v[30:33]
	v_mfma_f32_16x16x32_bf16 v[26:29], v[186:189], v[210:213], v[26:29]
	v_mfma_f32_16x16x32_bf16 v[26:29], v[190:193], v[214:217], v[26:29]
	v_mfma_f32_16x16x32_bf16 v[14:17], v[142:145], v[218:221], v[14:17]
	v_mfma_f32_16x16x32_bf16 v[14:17], v[182:185], v[222:225], v[14:17]
	v_mfma_f32_16x16x32_bf16 v[10:13], v[186:189], v[218:221], v[10:13]
	v_mfma_f32_16x16x32_bf16 v[10:13], v[190:193], v[222:225], v[10:13]
	s_setprio 0
	s_barrier
; #define PG8_STAGE(bufoff, gbase, voff) do { _Pragma("unroll") for (int _i = 0; _i < 2; ++_i) \
;         __builtin_amdgcn_global_load_lds((const unsigned*)((const char*)(gbase) + (voff)[_i]), (LAS unsigned*)(lds + (bufoff) + ldsw + _i * 8192), 16, 0, 0); } while (0)
; #define PG8_LDA(dst, b, h) do { _Pragma("unroll") for (int m = 0; m < 4; ++m) _Pragma("unroll") for (int k = 0; k < 2; ++k) dst[m][k] = *(const LAS bf16x8*)(lds + PG8_SA(b, h) + aoff + m * 2048 + k * 1024); } while (0)
; #define PG8_LDB(dst, b, h) do { _Pragma("unroll") for (int n = 0; n < 2; ++n) _Pragma("unroll") for (int k = 0; k < 2; ++k) dst[n][k] = *(const LAS bf16x8*)(lds + PG8_SB(b, h) + boff + n * 2048 + k * 1024); } while (0)
; #define PG8_MMA(ai, bj, At, Bt) do { __builtin_amdgcn_s_setprio(1); _Pragma("unroll") for (int m = 0; m < 4; ++m) _Pragma("unroll") for (int n = 0; n < 2; ++n) _Pragma("unroll") for (int k = 0; k < 2; ++k) \
;         acc[ai][bj][m][n] = __builtin_amdgcn_mfma_f32_16x16x32_bf16(Bt[n][k], At[m][k], acc[ai][bj][m][n], 0, 0, 0); __builtin_amdgcn_s_setprio(0); } while (0)
; #define PG8_WAIT_V(n) asm volatile("s_waitcnt vmcnt(" #n ")" ::: "memory")
; #define PG8_WAIT_L(n) asm volatile("s_waitcnt lgkmcnt(" #n ")" ::: "memory")
; #define PG8_BAR __builtin_amdgcn_s_barrier()
; #define PG8_SCHED __builtin_amdgcn_sched_barrier(0)
; template <class Epi, class Sched>
; __device__ __forceinline__ void gemm_phase(LAS unsigned char* lds, const Gemm g, const Sched& S, const Epi& E) {
;     ...
;             PG8_STAGE(PG8_SB(0, 1), b2 + hstep, voffB);
;             PG8_WAIT_V(6); PG8_BAR; PG8_MMA(1, 1, At, B1); PG8_BAR;
;             PG8_LDB(B0, 1, 0); PG8_SCHED; PG8_LDA(At, 1, 0); PG8_STAGE(PG8_SA(0, 1), a2 + hstep, voffA);
;             PG8_WAIT_L(8); PG8_BAR; PG8_WAIT_L(0); PG8_MMA(0, 0, At, B0); PG8_BAR; PG8_SCHED;
;             PG8_LDB(B1, 1, 1); PG8_STAGE(PG8_SB(1, 0), b3, voffB);
;             PG8_BAR; PG8_WAIT_L(0); PG8_MMA(0, 1, At, B1); PG8_BAR;
	s_add_u32 s24, s48, 0x40000
	s_addc_u32 s25, s49, 0
	s_add_i32 s39, s51, s94
	v_lshl_add_u64 v[142:143], s[24:25], 0, v[134:135]
	s_mov_b32 m0, s39
	s_nop 0
	global_load_lds_dwordx4 v[142:143], off
	v_lshl_add_u64 v[142:143], s[24:25], 0, v[130:131]
	s_add_i32 m0, s39, 0x2000
	s_nop 0
	global_load_lds_dwordx4 v[142:143], off
	s_waitcnt vmcnt(6)
	s_barrier
	s_setprio 1
	v_mfma_f32_16x16x32_bf16 v[54:57], v[226:229], v[194:197], v[54:57]
	v_mfma_f32_16x16x32_bf16 v[54:57], v[230:233], v[198:201], v[54:57]
	v_mfma_f32_16x16x32_bf16 v[50:53], v[234:237], v[194:197], v[50:53]
	v_mfma_f32_16x16x32_bf16 v[50:53], v[238:241], v[198:201], v[50:53]
	v_mfma_f32_16x16x32_bf16 v[38:41], v[226:229], v[202:205], v[38:41]
	v_mfma_f32_16x16x32_bf16 v[38:41], v[230:233], v[206:209], v[38:41]
	v_mfma_f32_16x16x32_bf16 v[34:37], v[234:237], v[202:205], v[34:37]
	v_mfma_f32_16x16x32_bf16 v[34:37], v[238:241], v[206:209], v[34:37]
	v_mfma_f32_16x16x32_bf16 v[22:25], v[226:229], v[210:213], v[22:25]
	v_mfma_f32_16x16x32_bf16 v[22:25], v[230:233], v[214:217], v[22:25]
	v_mfma_f32_16x16x32_bf16 v[18:21], v[234:237], v[210:213], v[18:21]
	v_mfma_f32_16x16x32_bf16 v[18:21], v[238:241], v[214:217], v[18:21]
	v_mfma_f32_16x16x32_bf16 v[6:9], v[226:229], v[218:221], v[6:9]
	v_mfma_f32_16x16x32_bf16 v[6:9], v[230:233], v[222:225], v[6:9]
	v_mfma_f32_16x16x32_bf16 v[2:5], v[234:237], v[218:221], v[2:5]
	v_mfma_f32_16x16x32_bf16 v[2:5], v[238:241], v[222:225], v[2:5]
	s_setprio 0
	s_add_i32 s39, 0, 0x18000
	v_add_u32_e32 v167, s39, v164
	s_barrier
	ds_read_b128 v[142:145], v167
	ds_read_b128 v[182:185], v167 offset:1024
	ds_read_b128 v[186:189], v167 offset:2048
	ds_read_b128 v[190:193], v167 offset:3072
	s_add_u32 s24, vcc_lo, 0x40000
	s_addc_u32 s25, vcc_hi, 0
	s_mov_b32 m0, s97
	v_lshl_add_u64 v[226:227], s[24:25], 0, v[136:137]
	ds_read_b128 v[194:197], v166 offset:32768
	ds_read_b128 v[198:201], v166 offset:33792
	ds_read_b128 v[202:205], v166 offset:34816
	ds_read_b128 v[206:209], v166 offset:35840
	ds_read_b128 v[210:213], v166 offset:36864
	ds_read_b128 v[214:217], v166 offset:37888
	ds_read_b128 v[218:221], v166 offset:38912
	ds_read_b128 v[222:225], v166 offset:39936
	global_load_lds_dwordx4 v[226:227], off
	v_lshl_add_u64 v[226:227], s[24:25], 0, v[132:133]
	s_mov_b32 m0, s98
	s_nop 0
	global_load_lds_dwordx4 v[226:227], off
	s_waitcnt lgkmcnt(8)
	s_barrier
	s_waitcnt lgkmcnt(0)
	s_setprio 1
	s_waitcnt lgkmcnt(0)
	v_mfma_f32_16x16x32_bf16 v[126:129], v[142:145], v[194:197], v[126:129]
	v_mfma_f32_16x16x32_bf16 v[126:129], v[182:185], v[198:201], v[126:129]
	v_mfma_f32_16x16x32_bf16 v[122:125], v[186:189], v[194:197], v[122:125]
	v_mfma_f32_16x16x32_bf16 v[122:125], v[190:193], v[198:201], v[122:125]
	v_mfma_f32_16x16x32_bf16 v[110:113], v[142:145], v[202:205], v[110:113]
	v_mfma_f32_16x16x32_bf16 v[110:113], v[182:185], v[206:209], v[110:113]
	v_mfma_f32_16x16x32_bf16 v[106:109], v[186:189], v[202:205], v[106:109]
	v_mfma_f32_16x16x32_bf16 v[106:109], v[190:193], v[206:209], v[106:109]
	v_mfma_f32_16x16x32_bf16 v[94:97], v[142:145], v[210:213], v[94:97]
	v_mfma_f32_16x16x32_bf16 v[94:97], v[182:185], v[214:217], v[94:97]
	v_mfma_f32_16x16x32_bf16 v[90:93], v[186:189], v[210:213], v[90:93]
	v_mfma_f32_16x16x32_bf16 v[90:93], v[190:193], v[214:217], v[90:93]
	v_mfma_f32_16x16x32_bf16 v[78:81], v[142:145], v[218:221], v[78:81]
	v_mfma_f32_16x16x32_bf16 v[78:81], v[182:185], v[222:225], v[78:81]
	v_mfma_f32_16x16x32_bf16 v[74:77], v[186:189], v[218:221], v[74:77]
	v_mfma_f32_16x16x32_bf16 v[74:77], v[190:193], v[222:225], v[74:77]
	s_setprio 0
	s_barrier
	s_add_i32 s51, 0, 0x1c000
	s_add_i32 s24, s39, s94
	v_add_u32_e32 v167, s51, v164
	v_lshl_add_u64 v[162:163], v[162:163], 0, s[12:13]
	s_mov_b32 m0, s24
	ds_read_b128 v[226:229], v167
	ds_read_b128 v[230:233], v167 offset:1024
	ds_read_b128 v[234:237], v167 offset:2048
	ds_read_b128 v[238:241], v167 offset:3072
	global_load_lds_dwordx4 v[162:163], off
	v_lshl_add_u64 v[162:163], v[168:169], 0, s[12:13]
	s_add_i32 m0, s24, 0x2000
	s_nop 0
	global_load_lds_dwordx4 v[162:163], off
	s_barrier
; #define PG8_STAGE(bufoff, gbase, voff) do { _Pragma("unroll") for (int _i = 0; _i < 2; ++_i) \
;         __builtin_amdgcn_global_load_lds((const unsigned*)((const char*)(gbase) + (voff)[_i]), (LAS unsigned*)(lds + (bufoff) + ldsw + _i * 8192), 16, 0, 0); } while (0)
; #define PG8_LDA(dst, b, h) do { _Pragma("unroll") for (int m = 0; m < 4; ++m) _Pragma("unroll") for (int k = 0; k < 2; ++k) dst[m][k] = *(const LAS bf16x8*)(lds + PG8_SA(b, h) + aoff + m * 2048 + k * 1024); } while (0)
; #define PG8_MMA(ai, bj, At, Bt) do { __builtin_amdgcn_s_setprio(1); _Pragma("unroll") for (int m = 0; m < 4; ++m) _Pragma("unroll") for (int n = 0; n < 2; ++n) _Pragma("unroll") for (int k = 0; k < 2; ++k) \
;         acc[ai][bj][m][n] = __builtin_amdgcn_mfma_f32_16x16x32_bf16(Bt[n][k], At[m][k], acc[ai][bj][m][n], 0, 0, 0); __builtin_amdgcn_s_setprio(0); } while (0)
; #define PG8_WAIT_V(n) asm volatile("s_waitcnt vmcnt(" #n ")" ::: "memory")
; #define PG8_WAIT_L(n) asm volatile("s_waitcnt lgkmcnt(" #n ")" ::: "memory")
; #define PG8_BAR __builtin_amdgcn_s_barrier()
; #define PG8_SCHED __builtin_amdgcn_sched_barrier(0)
; template <class Epi, class Sched>
; __device__ __forceinline__ void gemm_phase(LAS unsigned char* lds, const Gemm g, const Sched& S, const Epi& E) {
;     ...
;             PG8_LDA(At, 1, 1); PG8_STAGE(PG8_SA(1, 0), a3, voffA);
;             PG8_BAR; PG8_WAIT_L(0); PG8_MMA(1, 0, At, B0); PG8_BAR; PG8_SCHED;
;             PG8_STAGE(PG8_SB(1, 1), b3 + hstep, voffB);
;             PG8_WAIT_V(6); PG8_BAR; PG8_MMA(1, 1, At, B1); PG8_BAR;
;         }
;         if (wr == 0) PG8_BAR;
	s_waitcnt lgkmcnt(0)
	s_setprio 1
	s_waitcnt lgkmcnt(0)
	v_mfma_f32_16x16x32_bf16 v[118:121], v[226:229], v[194:197], v[118:121]
	v_mfma_f32_16x16x32_bf16 v[118:121], v[230:233], v[198:201], v[118:121]
	v_mfma_f32_16x16x32_bf16 v[114:117], v[234:237], v[194:197], v[114:117]
	v_mfma_f32_16x16x32_bf16 v[114:117], v[238:241], v[198:201], v[114:117]
	v_mfma_f32_16x16x32_bf16 v[102:105], v[226:229], v[202:205], v[102:105]
	v_mfma_f32_16x16x32_bf16 v[102:105], v[230:233], v[206:209], v[102:105]
	v_mfma_f32_16x16x32_bf16 v[98:101], v[234:237], v[202:205], v[98:101]
	v_mfma_f32_16x16x32_bf16 v[98:101], v[238:241], v[206:209], v[98:101]
	v_mfma_f32_16x16x32_bf16 v[86:89], v[226:229], v[210:213], v[86:89]
	v_mfma_f32_16x16x32_bf16 v[86:89], v[230:233], v[214:217], v[86:89]
	v_mfma_f32_16x16x32_bf16 v[82:85], v[234:237], v[210:213], v[82:85]
	v_mfma_f32_16x16x32_bf16 v[82:85], v[238:241], v[214:217], v[82:85]
	v_mfma_f32_16x16x32_bf16 v[70:73], v[226:229], v[218:221], v[70:73]
	v_mfma_f32_16x16x32_bf16 v[70:73], v[230:233], v[222:225], v[70:73]
	v_mfma_f32_16x16x32_bf16 v[66:69], v[234:237], v[218:221], v[66:69]
	v_mfma_f32_16x16x32_bf16 v[66:69], v[238:241], v[222:225], v[66:69]
	s_setprio 0
	s_mov_b32 m0, s99
	v_lshl_add_u64 v[162:163], v[242:243], 0, s[12:13]
	s_barrier
	ds_read_b128 v[194:197], v166 offset:49152
	ds_read_b128 v[198:201], v166 offset:50176
	ds_read_b128 v[202:205], v166 offset:51200
	ds_read_b128 v[206:209], v166 offset:52224
	ds_read_b128 v[210:213], v166 offset:53248
	ds_read_b128 v[214:217], v166 offset:54272
	ds_read_b128 v[218:221], v166 offset:55296
	ds_read_b128 v[222:225], v166 offset:56320
	global_load_lds_dwordx4 v[162:163], off
	v_lshl_add_u64 v[162:163], v[244:245], 0, s[12:13]
	s_mov_b32 m0, s82
	s_nop 0
	global_load_lds_dwordx4 v[162:163], off
	s_barrier
	s_waitcnt lgkmcnt(0)
	s_setprio 1
	s_waitcnt lgkmcnt(0)
	v_mfma_f32_16x16x32_bf16 v[62:65], v[142:145], v[194:197], v[62:65]
	v_mfma_f32_16x16x32_bf16 v[62:65], v[182:185], v[198:201], v[62:65]
	v_mfma_f32_16x16x32_bf16 v[58:61], v[186:189], v[194:197], v[58:61]
	v_mfma_f32_16x16x32_bf16 v[58:61], v[190:193], v[198:201], v[58:61]
	v_mfma_f32_16x16x32_bf16 v[46:49], v[142:145], v[202:205], v[46:49]
	v_mfma_f32_16x16x32_bf16 v[46:49], v[182:185], v[206:209], v[46:49]
	v_mfma_f32_16x16x32_bf16 v[42:45], v[186:189], v[202:205], v[42:45]
	v_mfma_f32_16x16x32_bf16 v[42:45], v[190:193], v[206:209], v[42:45]
	v_mfma_f32_16x16x32_bf16 v[30:33], v[142:145], v[210:213], v[30:33]
	v_mfma_f32_16x16x32_bf16 v[30:33], v[182:185], v[214:217], v[30:33]
	v_mfma_f32_16x16x32_bf16 v[26:29], v[186:189], v[210:213], v[26:29]
	v_mfma_f32_16x16x32_bf16 v[26:29], v[190:193], v[214:217], v[26:29]
	v_mfma_f32_16x16x32_bf16 v[14:17], v[142:145], v[218:221], v[14:17]
	v_mfma_f32_16x16x32_bf16 v[14:17], v[182:185], v[222:225], v[14:17]
	v_mfma_f32_16x16x32_bf16 v[10:13], v[186:189], v[218:221], v[10:13]
	v_mfma_f32_16x16x32_bf16 v[10:13], v[190:193], v[222:225], v[10:13]
	s_setprio 0
	s_barrier
	s_add_u32 s24, s48, 0x40080
	s_addc_u32 s25, s49, 0
	s_add_i32 s39, s51, s94
	v_lshl_add_u64 v[142:143], s[24:25], 0, v[134:135]
	s_mov_b32 m0, s39
	s_nop 0
	global_load_lds_dwordx4 v[142:143], off
	v_lshl_add_u64 v[142:143], s[24:25], 0, v[130:131]
	s_add_i32 m0, s39, 0x2000
	s_nop 0
	global_load_lds_dwordx4 v[142:143], off
	s_waitcnt vmcnt(6)
	s_barrier
	s_setprio 1
	v_mfma_f32_16x16x32_bf16 v[54:57], v[226:229], v[194:197], v[54:57]
	v_mfma_f32_16x16x32_bf16 v[54:57], v[230:233], v[198:201], v[54:57]
	v_mfma_f32_16x16x32_bf16 v[50:53], v[234:237], v[194:197], v[50:53]
	v_mfma_f32_16x16x32_bf16 v[50:53], v[238:241], v[198:201], v[50:53]
	v_mfma_f32_16x16x32_bf16 v[38:41], v[226:229], v[202:205], v[38:41]
	v_mfma_f32_16x16x32_bf16 v[38:41], v[230:233], v[206:209], v[38:41]
	v_mfma_f32_16x16x32_bf16 v[34:37], v[234:237], v[202:205], v[34:37]
	v_mfma_f32_16x16x32_bf16 v[34:37], v[238:241], v[206:209], v[34:37]
	v_mfma_f32_16x16x32_bf16 v[22:25], v[226:229], v[210:213], v[22:25]
	v_mfma_f32_16x16x32_bf16 v[22:25], v[230:233], v[214:217], v[22:25]
	v_mfma_f32_16x16x32_bf16 v[18:21], v[234:237], v[210:213], v[18:21]
	v_mfma_f32_16x16x32_bf16 v[18:21], v[238:241], v[214:217], v[18:21]
	v_mfma_f32_16x16x32_bf16 v[6:9], v[226:229], v[218:221], v[6:9]
	v_mfma_f32_16x16x32_bf16 v[6:9], v[230:233], v[222:225], v[6:9]
	v_mfma_f32_16x16x32_bf16 v[2:5], v[234:237], v[218:221], v[2:5]
	v_mfma_f32_16x16x32_bf16 v[2:5], v[238:241], v[222:225], v[2:5]
	s_setprio 0
	s_add_i32 s38, s38, 2
	s_add_u32 s35, s35, 0x100
	s_addc_u32 s50, s50, 0
	s_add_u32 s0, s0, 0x100
	s_addc_u32 s1, s1, 0
	s_cmp_gt_u32 s38, 13
	s_barrier
	s_cbranch_scc0 .LBB0_557
	s_and_b64 vcc, exec, s[42:43]
	s_cbranch_vccz .LBB0_560
	s_barrier

; #define PG8_STAGE(bufoff, gbase, voff) do { _Pragma("unroll") for (int _i = 0; _i < 2; ++_i) \
;         __builtin_amdgcn_global_load_lds((const unsigned*)((const char*)(gbase) + (voff)[_i]), (LAS unsigned*)(lds + (bufoff) + ldsw + _i * 8192), 16, 0, 0); } while (0)
; #define PG8_LDA(dst, b, h) do { _Pragma("unroll") for (int m = 0; m < 4; ++m) _Pragma("unroll") for (int k = 0; k < 2; ++k) dst[m][k] = *(const LAS bf16x8*)(lds + PG8_SA(b, h) + aoff + m * 2048 + k * 1024); } while (0)
; #define PG8_LDB(dst, b, h) do { _Pragma("unroll") for (int n = 0; n < 2; ++n) _Pragma("unroll") for (int k = 0; k < 2; ++k) dst[n][k] = *(const LAS bf16x8*)(lds + PG8_SB(b, h) + boff + n * 2048 + k * 1024); } while (0)
; #define PG8_MMA(ai, bj, At, Bt) do { __builtin_amdgcn_s_setprio(1); _Pragma("unroll") for (int m = 0; m < 4; ++m) _Pragma("unroll") for (int n = 0; n < 2; ++n) _Pragma("unroll") for (int k = 0; k < 2; ++k) \
;         acc[ai][bj][m][n] = __builtin_amdgcn_mfma_f32_16x16x32_bf16(Bt[n][k], At[m][k], acc[ai][bj][m][n], 0, 0, 0); __builtin_amdgcn_s_setprio(0); } while (0)
; #define PG8_WAIT_L(n) asm volatile("s_waitcnt lgkmcnt(" #n ")" ::: "memory")
; #define PG8_BAR __builtin_amdgcn_s_barrier()
; #define PG8_SCHED __builtin_amdgcn_sched_barrier(0)
; template <class Epi, class Sched>
; __device__ __forceinline__ void gemm_phase(LAS unsigned char* lds, const Gemm g, const Sched& S, const Epi& E) {
;     ...
;         for (int t = 0; t < nt; t += 2) {
;             const bool last = (t == nt - 2);
;             const char* a1 = cA + (size_t)(t + 1) * kstep;
;             const char* a2 = last ? nA : cA + (size_t)(t + 2) * kstep; const char* b2 = last ? nB : cB + (size_t)(t + 2) * kstep;
;             const char* a3 = a2 + kstep; const char* b3 = b2 + kstep;
;             PG8_LDB(B0, 0, 0); PG8_SCHED; PG8_LDA(At, 0, 0); PG8_STAGE(PG8_SA(1, 1), a1 + hstep, voffA);
;             PG8_WAIT_L(8); PG8_BAR; PG8_WAIT_L(0); PG8_MMA(0, 0, At, B0); PG8_BAR; PG8_SCHED;
;             PG8_LDB(B1, 0, 1); PG8_STAGE(PG8_SB(0, 0), b2, voffB);
;             PG8_BAR; PG8_WAIT_L(0); PG8_MMA(0, 1, At, B1); PG8_BAR;
;             PG8_LDA(At, 0, 1); PG8_STAGE(PG8_SA(0, 0), a2, voffA);
;             PG8_BAR; PG8_WAIT_L(0); PG8_MMA(1, 0, At, B0); PG8_BAR; PG8_SCHED;
.LBB0_627:
	s_add_u32 s24, s0, 0xfff00080
	s_addc_u32 s25, s1, -1
	s_add_i32 s51, 0, 0x10000
	v_add_u32_e32 v142, s51, v144
	ds_read_b128 v[164:167], v142
	ds_read_b128 v[182:185], v142 offset:1024
	ds_read_b128 v[186:189], v142 offset:2048
	ds_read_b128 v[190:193], v142 offset:3072
	s_cmp_eq_u32 s98, 60
	s_cselect_b32 s77, s47, s25
	s_cselect_b32 s76, s46, s24
	s_cselect_b32 s49, s43, s50
	s_cselect_b32 s48, s45, s35
	v_lshl_add_u64 v[142:143], s[0:1], 0, v[140:141]
	s_add_i32 m0, s86, 0xc000
	ds_read_b128 v[194:197], v162
	ds_read_b128 v[198:201], v162 offset:1024
	ds_read_b128 v[202:205], v162 offset:2048
	ds_read_b128 v[206:209], v162 offset:3072
	ds_read_b128 v[210:213], v162 offset:4096
	ds_read_b128 v[214:217], v162 offset:5120
	ds_read_b128 v[218:221], v162 offset:6144
	ds_read_b128 v[222:225], v162 offset:7168
	global_load_lds_dwordx4 v[142:143], off
	v_lshl_add_u64 v[142:143], s[0:1], 0, v[138:139]
	s_add_i32 m0, s86, 0xe000
	s_nop 0
	global_load_lds_dwordx4 v[142:143], off
	s_waitcnt lgkmcnt(8)
	s_barrier
	s_waitcnt lgkmcnt(0)
	s_setprio 1
	s_waitcnt lgkmcnt(0)
	v_mfma_f32_16x16x32_bf16 v[126:129], v[164:167], v[194:197], v[126:129]
	v_mfma_f32_16x16x32_bf16 v[126:129], v[182:185], v[198:201], v[126:129]
	v_mfma_f32_16x16x32_bf16 v[122:125], v[186:189], v[194:197], v[122:125]
	v_mfma_f32_16x16x32_bf16 v[122:125], v[190:193], v[198:201], v[122:125]
	v_mfma_f32_16x16x32_bf16 v[118:121], v[164:167], v[202:205], v[118:121]
	v_mfma_f32_16x16x32_bf16 v[118:121], v[182:185], v[206:209], v[118:121]
	v_mfma_f32_16x16x32_bf16 v[110:113], v[186:189], v[202:205], v[110:113]
	v_mfma_f32_16x16x32_bf16 v[110:113], v[190:193], v[206:209], v[110:113]
	v_mfma_f32_16x16x32_bf16 v[102:105], v[164:167], v[210:213], v[102:105]
	v_mfma_f32_16x16x32_bf16 v[102:105], v[182:185], v[214:217], v[102:105]
	v_mfma_f32_16x16x32_bf16 v[94:97], v[186:189], v[210:213], v[94:97]
	v_mfma_f32_16x16x32_bf16 v[94:97], v[190:193], v[214:217], v[94:97]
	v_mfma_f32_16x16x32_bf16 v[86:89], v[164:167], v[218:221], v[86:89]
	v_mfma_f32_16x16x32_bf16 v[86:89], v[182:185], v[222:225], v[86:89]
	v_mfma_f32_16x16x32_bf16 v[78:81], v[186:189], v[218:221], v[78:81]
	v_mfma_f32_16x16x32_bf16 v[78:81], v[190:193], v[222:225], v[78:81]
	s_setprio 0
	s_barrier
	s_add_i32 s99, 0, 0x14000
	v_add_u32_e32 v142, s99, v144
	s_add_i32 s24, s51, s83
	ds_read_b128 v[226:229], v142
	ds_read_b128 v[230:233], v142 offset:1024
	ds_read_b128 v[234:237], v142 offset:2048
	ds_read_b128 v[238:241], v142 offset:3072
	v_lshl_add_u64 v[142:143], s[48:49], 0, v[134:135]
	s_mov_b32 m0, s24
	v_lshl_add_u64 v[168:169], s[48:49], 0, v[130:131]
	global_load_lds_dwordx4 v[142:143], off
	s_add_i32 m0, s24, 0x2000
	s_nop 0
	global_load_lds_dwordx4 v[168:169], off
	s_barrier
	s_waitcnt lgkmcnt(0)
	s_setprio 1
	s_waitcnt lgkmcnt(0)
	v_mfma_f32_16x16x32_bf16 v[114:117], v[226:229], v[194:197], v[114:117]
	v_mfma_f32_16x16x32_bf16 v[114:117], v[230:233], v[198:201], v[114:117]
	v_mfma_f32_16x16x32_bf16 v[106:109], v[234:237], v[194:197], v[106:109]
	v_mfma_f32_16x16x32_bf16 v[106:109], v[238:241], v[198:201], v[106:109]
	v_mfma_f32_16x16x32_bf16 v[98:101], v[226:229], v[202:205], v[98:101]
	v_mfma_f32_16x16x32_bf16 v[98:101], v[230:233], v[206:209], v[98:101]
	v_mfma_f32_16x16x32_bf16 v[90:93], v[234:237], v[202:205], v[90:93]
	v_mfma_f32_16x16x32_bf16 v[90:93], v[238:241], v[206:209], v[90:93]
	v_mfma_f32_16x16x32_bf16 v[82:85], v[226:229], v[210:213], v[82:85]
	v_mfma_f32_16x16x32_bf16 v[82:85], v[230:233], v[214:217], v[82:85]
	v_mfma_f32_16x16x32_bf16 v[74:77], v[234:237], v[210:213], v[74:77]
	v_mfma_f32_16x16x32_bf16 v[74:77], v[238:241], v[214:217], v[74:77]
	v_mfma_f32_16x16x32_bf16 v[70:73], v[226:229], v[218:221], v[70:73]
	v_mfma_f32_16x16x32_bf16 v[70:73], v[230:233], v[222:225], v[70:73]
	v_mfma_f32_16x16x32_bf16 v[66:69], v[234:237], v[218:221], v[66:69]
	v_mfma_f32_16x16x32_bf16 v[66:69], v[238:241], v[222:225], v[66:69]
	s_setprio 0
	s_mov_b32 m0, s86
	v_lshl_add_u64 v[242:243], s[76:77], 0, v[136:137]
	s_barrier
	ds_read_b128 v[194:197], v162 offset:16384
	ds_read_b128 v[198:201], v162 offset:17408
	ds_read_b128 v[202:205], v162 offset:18432
	ds_read_b128 v[206:209], v162 offset:19456
	ds_read_b128 v[210:213], v162 offset:20480
	ds_read_b128 v[214:217], v162 offset:21504
	ds_read_b128 v[218:221], v162 offset:22528
	ds_read_b128 v[222:225], v162 offset:23552
	global_load_lds_dwordx4 v[242:243], off
	v_lshl_add_u64 v[244:245], s[76:77], 0, v[132:133]
	s_mov_b32 m0, s92
	s_nop 0
	global_load_lds_dwordx4 v[244:245], off
	s_barrier
	s_waitcnt lgkmcnt(0)
	s_setprio 1
	s_waitcnt lgkmcnt(0)
	v_mfma_f32_16x16x32_bf16 v[62:65], v[164:167], v[194:197], v[62:65]
	v_mfma_f32_16x16x32_bf16 v[62:65], v[182:185], v[198:201], v[62:65]
	v_mfma_f32_16x16x32_bf16 v[58:61], v[186:189], v[194:197], v[58:61]
	v_mfma_f32_16x16x32_bf16 v[58:61], v[190:193], v[198:201], v[58:61]
	v_mfma_f32_16x16x32_bf16 v[54:57], v[164:167], v[202:205], v[54:57]
	v_mfma_f32_16x16x32_bf16 v[54:57], v[182:185], v[206:209], v[54:57]
	v_mfma_f32_16x16x32_bf16 v[46:49], v[186:189], v[202:205], v[46:49]
	v_mfma_f32_16x16x32_bf16 v[46:49], v[190:193], v[206:209], v[46:49]
	v_mfma_f32_16x16x32_bf16 v[38:41], v[164:167], v[210:213], v[38:41]
	v_mfma_f32_16x16x32_bf16 v[38:41], v[182:185], v[214:217], v[38:41]
	v_mfma_f32_16x16x32_bf16 v[30:33], v[186:189], v[210:213], v[30:33]
	v_mfma_f32_16x16x32_bf16 v[30:33], v[190:193], v[214:217], v[30:33]
	v_mfma_f32_16x16x32_bf16 v[22:25], v[164:167], v[218:221], v[22:25]
	v_mfma_f32_16x16x32_bf16 v[22:25], v[182:185], v[222:225], v[22:25]
	v_mfma_f32_16x16x32_bf16 v[14:17], v[186:189], v[218:221], v[14:17]
	v_mfma_f32_16x16x32_bf16 v[14:17], v[190:193], v[222:225], v[14:17]
	s_setprio 0
	s_barrier
; #define PG8_STAGE(bufoff, gbase, voff) do { _Pragma("unroll") for (int _i = 0; _i < 2; ++_i) \
;         __builtin_amdgcn_global_load_lds((const unsigned*)((const char*)(gbase) + (voff)[_i]), (LAS unsigned*)(lds + (bufoff) + ldsw + _i * 8192), 16, 0, 0); } while (0)
; #define PG8_LDA(dst, b, h) do { _Pragma("unroll") for (int m = 0; m < 4; ++m) _Pragma("unroll") for (int k = 0; k < 2; ++k) dst[m][k] = *(const LAS bf16x8*)(lds + PG8_SA(b, h) + aoff + m * 2048 + k * 1024); } while (0)
; #define PG8_LDB(dst, b, h) do { _Pragma("unroll") for (int n = 0; n < 2; ++n) _Pragma("unroll") for (int k = 0; k < 2; ++k) dst[n][k] = *(const LAS bf16x8*)(lds + PG8_SB(b, h) + boff + n * 2048 + k * 1024); } while (0)
; #define PG8_MMA(ai, bj, At, Bt) do { __builtin_amdgcn_s_setprio(1); _Pragma("unroll") for (int m = 0; m < 4; ++m) _Pragma("unroll") for (int n = 0; n < 2; ++n) _Pragma("unroll") for (int k = 0; k < 2; ++k) \
;         acc[ai][bj][m][n] = __builtin_amdgcn_mfma_f32_16x16x32_bf16(Bt[n][k], At[m][k], acc[ai][bj][m][n], 0, 0, 0); __builtin_amdgcn_s_setprio(0); } while (0)
; #define PG8_WAIT_V(n) asm volatile("s_waitcnt vmcnt(" #n ")" ::: "memory")
; #define PG8_WAIT_L(n) asm volatile("s_waitcnt lgkmcnt(" #n ")" ::: "memory")
; #define PG8_BAR __builtin_amdgcn_s_barrier()
; #define PG8_SCHED __builtin_amdgcn_sched_barrier(0)
; template <class Epi, class Sched>
; __device__ __forceinline__ void gemm_phase(LAS unsigned char* lds, const Gemm g, const Sched& S, const Epi& E) {
;     ...
;             PG8_STAGE(PG8_SB(0, 1), b2 + hstep, voffB);
;             PG8_WAIT_V(6); PG8_BAR; PG8_MMA(1, 1, At, B1); PG8_BAR;
;             PG8_LDB(B0, 1, 0); PG8_SCHED; PG8_LDA(At, 1, 0); PG8_STAGE(PG8_SA(0, 1), a2 + hstep, voffA);
;             PG8_WAIT_L(8); PG8_BAR; PG8_WAIT_L(0); PG8_MMA(0, 0, At, B0); PG8_BAR; PG8_SCHED;
;             PG8_LDB(B1, 1, 1); PG8_STAGE(PG8_SB(1, 0), b3, voffB);
;             PG8_BAR; PG8_WAIT_L(0); PG8_MMA(0, 1, At, B1); PG8_BAR;
	s_add_u32 s24, s48, 0x100000
	s_addc_u32 s25, s49, 0
	s_add_i32 s51, s99, s83
	v_lshl_add_u64 v[164:165], s[24:25], 0, v[134:135]
	s_mov_b32 m0, s51
	s_nop 0
	global_load_lds_dwordx4 v[164:165], off
	v_lshl_add_u64 v[164:165], s[24:25], 0, v[130:131]
	s_add_i32 m0, s51, 0x2000
	s_nop 0
	global_load_lds_dwordx4 v[164:165], off
	s_waitcnt vmcnt(6)
	s_barrier
	s_setprio 1
	v_mfma_f32_16x16x32_bf16 v[50:53], v[226:229], v[194:197], v[50:53]
	v_mfma_f32_16x16x32_bf16 v[50:53], v[230:233], v[198:201], v[50:53]
	v_mfma_f32_16x16x32_bf16 v[42:45], v[234:237], v[194:197], v[42:45]
	v_mfma_f32_16x16x32_bf16 v[42:45], v[238:241], v[198:201], v[42:45]
	v_mfma_f32_16x16x32_bf16 v[34:37], v[226:229], v[202:205], v[34:37]
	v_mfma_f32_16x16x32_bf16 v[34:37], v[230:233], v[206:209], v[34:37]
	v_mfma_f32_16x16x32_bf16 v[26:29], v[234:237], v[202:205], v[26:29]
	v_mfma_f32_16x16x32_bf16 v[26:29], v[238:241], v[206:209], v[26:29]
	v_mfma_f32_16x16x32_bf16 v[18:21], v[226:229], v[210:213], v[18:21]
	v_mfma_f32_16x16x32_bf16 v[18:21], v[230:233], v[214:217], v[18:21]
	v_mfma_f32_16x16x32_bf16 v[10:13], v[234:237], v[210:213], v[10:13]
	v_mfma_f32_16x16x32_bf16 v[10:13], v[238:241], v[214:217], v[10:13]
	v_mfma_f32_16x16x32_bf16 v[6:9], v[226:229], v[218:221], v[6:9]
	v_mfma_f32_16x16x32_bf16 v[6:9], v[230:233], v[222:225], v[6:9]
	v_mfma_f32_16x16x32_bf16 v[2:5], v[234:237], v[218:221], v[2:5]
	v_mfma_f32_16x16x32_bf16 v[2:5], v[238:241], v[222:225], v[2:5]
	s_setprio 0
	s_add_i32 s51, 0, 0x18000
	v_add_u32_e32 v163, s51, v144
	s_barrier
	ds_read_b128 v[164:167], v163
	ds_read_b128 v[182:185], v163 offset:1024
	ds_read_b128 v[186:189], v163 offset:2048
	ds_read_b128 v[190:193], v163 offset:3072
	s_add_u32 s24, s76, 0x100000
	s_addc_u32 s25, s77, 0
	s_mov_b32 m0, s93
	v_lshl_add_u64 v[226:227], s[24:25], 0, v[136:137]
	ds_read_b128 v[194:197], v162 offset:32768
	ds_read_b128 v[198:201], v162 offset:33792
	ds_read_b128 v[202:205], v162 offset:34816
	ds_read_b128 v[206:209], v162 offset:35840
	ds_read_b128 v[210:213], v162 offset:36864
	ds_read_b128 v[214:217], v162 offset:37888
	ds_read_b128 v[218:221], v162 offset:38912
	ds_read_b128 v[222:225], v162 offset:39936
	global_load_lds_dwordx4 v[226:227], off
	v_lshl_add_u64 v[226:227], s[24:25], 0, v[132:133]
	s_mov_b32 m0, s94
	s_nop 0
	global_load_lds_dwordx4 v[226:227], off
	s_waitcnt lgkmcnt(8)
	s_barrier
	s_waitcnt lgkmcnt(0)
	s_setprio 1
	s_waitcnt lgkmcnt(0)
	v_mfma_f32_16x16x32_bf16 v[126:129], v[164:167], v[194:197], v[126:129]
	v_mfma_f32_16x16x32_bf16 v[126:129], v[182:185], v[198:201], v[126:129]
	v_mfma_f32_16x16x32_bf16 v[122:125], v[186:189], v[194:197], v[122:125]
	v_mfma_f32_16x16x32_bf16 v[122:125], v[190:193], v[198:201], v[122:125]
	v_mfma_f32_16x16x32_bf16 v[118:121], v[164:167], v[202:205], v[118:121]
	v_mfma_f32_16x16x32_bf16 v[118:121], v[182:185], v[206:209], v[118:121]
	v_mfma_f32_16x16x32_bf16 v[110:113], v[186:189], v[202:205], v[110:113]
	v_mfma_f32_16x16x32_bf16 v[110:113], v[190:193], v[206:209], v[110:113]
	v_mfma_f32_16x16x32_bf16 v[102:105], v[164:167], v[210:213], v[102:105]
	v_mfma_f32_16x16x32_bf16 v[102:105], v[182:185], v[214:217], v[102:105]
	v_mfma_f32_16x16x32_bf16 v[94:97], v[186:189], v[210:213], v[94:97]
	v_mfma_f32_16x16x32_bf16 v[94:97], v[190:193], v[214:217], v[94:97]
	v_mfma_f32_16x16x32_bf16 v[86:89], v[164:167], v[218:221], v[86:89]
	v_mfma_f32_16x16x32_bf16 v[86:89], v[182:185], v[222:225], v[86:89]
	v_mfma_f32_16x16x32_bf16 v[78:81], v[186:189], v[218:221], v[78:81]
	v_mfma_f32_16x16x32_bf16 v[78:81], v[190:193], v[222:225], v[78:81]
	s_setprio 0
	s_barrier
	s_add_i32 s76, 0, 0x1c000
	s_add_i32 s24, s51, s83
	v_add_u32_e32 v163, s76, v144
	v_lshl_add_u64 v[142:143], v[142:143], 0, s[12:13]
	s_mov_b32 m0, s24
	ds_read_b128 v[226:229], v163
	ds_read_b128 v[230:233], v163 offset:1024
	ds_read_b128 v[234:237], v163 offset:2048
	ds_read_b128 v[238:241], v163 offset:3072
	global_load_lds_dwordx4 v[142:143], off
	v_lshl_add_u64 v[142:143], v[168:169], 0, s[12:13]
	s_add_i32 m0, s24, 0x2000
	s_nop 0
	global_load_lds_dwordx4 v[142:143], off
	s_barrier
; #define PG8_STAGE(bufoff, gbase, voff) do { _Pragma("unroll") for (int _i = 0; _i < 2; ++_i) \
;         __builtin_amdgcn_global_load_lds((const unsigned*)((const char*)(gbase) + (voff)[_i]), (LAS unsigned*)(lds + (bufoff) + ldsw + _i * 8192), 16, 0, 0); } while (0)
; #define PG8_LDA(dst, b, h) do { _Pragma("unroll") for (int m = 0; m < 4; ++m) _Pragma("unroll") for (int k = 0; k < 2; ++k) dst[m][k] = *(const LAS bf16x8*)(lds + PG8_SA(b, h) + aoff + m * 2048 + k * 1024); } while (0)
; #define PG8_MMA(ai, bj, At, Bt) do { __builtin_amdgcn_s_setprio(1); _Pragma("unroll") for (int m = 0; m < 4; ++m) _Pragma("unroll") for (int n = 0; n < 2; ++n) _Pragma("unroll") for (int k = 0; k < 2; ++k) \
;         acc[ai][bj][m][n] = __builtin_amdgcn_mfma_f32_16x16x32_bf16(Bt[n][k], At[m][k], acc[ai][bj][m][n], 0, 0, 0); __builtin_amdgcn_s_setprio(0); } while (0)
; #define PG8_WAIT_V(n) asm volatile("s_waitcnt vmcnt(" #n ")" ::: "memory")
; #define PG8_WAIT_L(n) asm volatile("s_waitcnt lgkmcnt(" #n ")" ::: "memory")
; #define PG8_BAR __builtin_amdgcn_s_barrier()
; #define PG8_SCHED __builtin_amdgcn_sched_barrier(0)
; template <class Epi, class Sched>
; __device__ __forceinline__ void gemm_phase(LAS unsigned char* lds, const Gemm g, const Sched& S, const Epi& E) {
;     ...
;             PG8_LDA(At, 1, 1); PG8_STAGE(PG8_SA(1, 0), a3, voffA);
;             PG8_BAR; PG8_WAIT_L(0); PG8_MMA(1, 0, At, B0); PG8_BAR; PG8_SCHED;
;             PG8_STAGE(PG8_SB(1, 1), b3 + hstep, voffB);
;             PG8_WAIT_V(6); PG8_BAR; PG8_MMA(1, 1, At, B1); PG8_BAR;
;         }
;         if (wr == 0) PG8_BAR;
	s_waitcnt lgkmcnt(0)
	s_setprio 1
	s_waitcnt lgkmcnt(0)
	v_mfma_f32_16x16x32_bf16 v[114:117], v[226:229], v[194:197], v[114:117]
	v_mfma_f32_16x16x32_bf16 v[114:117], v[230:233], v[198:201], v[114:117]
	v_mfma_f32_16x16x32_bf16 v[106:109], v[234:237], v[194:197], v[106:109]
	v_mfma_f32_16x16x32_bf16 v[106:109], v[238:241], v[198:201], v[106:109]
	v_mfma_f32_16x16x32_bf16 v[98:101], v[226:229], v[202:205], v[98:101]
	v_mfma_f32_16x16x32_bf16 v[98:101], v[230:233], v[206:209], v[98:101]
	v_mfma_f32_16x16x32_bf16 v[90:93], v[234:237], v[202:205], v[90:93]
	v_mfma_f32_16x16x32_bf16 v[90:93], v[238:241], v[206:209], v[90:93]
	v_mfma_f32_16x16x32_bf16 v[82:85], v[226:229], v[210:213], v[82:85]
	v_mfma_f32_16x16x32_bf16 v[82:85], v[230:233], v[214:217], v[82:85]
	v_mfma_f32_16x16x32_bf16 v[74:77], v[234:237], v[210:213], v[74:77]
	v_mfma_f32_16x16x32_bf16 v[74:77], v[238:241], v[214:217], v[74:77]
	v_mfma_f32_16x16x32_bf16 v[70:73], v[226:229], v[218:221], v[70:73]
	v_mfma_f32_16x16x32_bf16 v[70:73], v[230:233], v[222:225], v[70:73]
	v_mfma_f32_16x16x32_bf16 v[66:69], v[234:237], v[218:221], v[66:69]
	v_mfma_f32_16x16x32_bf16 v[66:69], v[238:241], v[222:225], v[66:69]
	s_setprio 0
	s_mov_b32 m0, s95
	v_lshl_add_u64 v[142:143], v[242:243], 0, s[12:13]
	s_barrier
	ds_read_b128 v[194:197], v162 offset:49152
	ds_read_b128 v[198:201], v162 offset:50176
	ds_read_b128 v[202:205], v162 offset:51200
	ds_read_b128 v[206:209], v162 offset:52224
	ds_read_b128 v[210:213], v162 offset:53248
	ds_read_b128 v[214:217], v162 offset:54272
	ds_read_b128 v[218:221], v162 offset:55296
	ds_read_b128 v[222:225], v162 offset:56320
	global_load_lds_dwordx4 v[142:143], off
	v_lshl_add_u64 v[142:143], v[244:245], 0, s[12:13]
	s_mov_b32 m0, s96
	s_nop 0
	global_load_lds_dwordx4 v[142:143], off
	s_barrier
	s_waitcnt lgkmcnt(0)
	s_setprio 1
	s_waitcnt lgkmcnt(0)
	v_mfma_f32_16x16x32_bf16 v[62:65], v[164:167], v[194:197], v[62:65]
	v_mfma_f32_16x16x32_bf16 v[62:65], v[182:185], v[198:201], v[62:65]
	v_mfma_f32_16x16x32_bf16 v[58:61], v[186:189], v[194:197], v[58:61]
	v_mfma_f32_16x16x32_bf16 v[58:61], v[190:193], v[198:201], v[58:61]
	v_mfma_f32_16x16x32_bf16 v[54:57], v[164:167], v[202:205], v[54:57]
	v_mfma_f32_16x16x32_bf16 v[54:57], v[182:185], v[206:209], v[54:57]
	v_mfma_f32_16x16x32_bf16 v[46:49], v[186:189], v[202:205], v[46:49]
	v_mfma_f32_16x16x32_bf16 v[46:49], v[190:193], v[206:209], v[46:49]
	v_mfma_f32_16x16x32_bf16 v[38:41], v[164:167], v[210:213], v[38:41]
	v_mfma_f32_16x16x32_bf16 v[38:41], v[182:185], v[214:217], v[38:41]
	v_mfma_f32_16x16x32_bf16 v[30:33], v[186:189], v[210:213], v[30:33]
	v_mfma_f32_16x16x32_bf16 v[30:33], v[190:193], v[214:217], v[30:33]
	v_mfma_f32_16x16x32_bf16 v[22:25], v[164:167], v[218:221], v[22:25]
	v_mfma_f32_16x16x32_bf16 v[22:25], v[182:185], v[222:225], v[22:25]
	v_mfma_f32_16x16x32_bf16 v[14:17], v[186:189], v[218:221], v[14:17]
	v_mfma_f32_16x16x32_bf16 v[14:17], v[190:193], v[222:225], v[14:17]
	s_setprio 0
	s_barrier
	s_add_u32 s24, s48, 0x100080
	s_addc_u32 s25, s49, 0
	s_add_i32 s48, s76, s83
	v_lshl_add_u64 v[142:143], s[24:25], 0, v[134:135]
	s_mov_b32 m0, s48
	s_nop 0
	global_load_lds_dwordx4 v[142:143], off
	v_lshl_add_u64 v[142:143], s[24:25], 0, v[130:131]
	s_add_i32 m0, s48, 0x2000
	s_nop 0
	global_load_lds_dwordx4 v[142:143], off
	s_waitcnt vmcnt(6)
	s_barrier
	s_setprio 1
	v_mfma_f32_16x16x32_bf16 v[50:53], v[226:229], v[194:197], v[50:53]
	v_mfma_f32_16x16x32_bf16 v[50:53], v[230:233], v[198:201], v[50:53]
	v_mfma_f32_16x16x32_bf16 v[42:45], v[234:237], v[194:197], v[42:45]
	v_mfma_f32_16x16x32_bf16 v[42:45], v[238:241], v[198:201], v[42:45]
	v_mfma_f32_16x16x32_bf16 v[34:37], v[226:229], v[202:205], v[34:37]
	v_mfma_f32_16x16x32_bf16 v[34:37], v[230:233], v[206:209], v[34:37]
	v_mfma_f32_16x16x32_bf16 v[26:29], v[234:237], v[202:205], v[26:29]
	v_mfma_f32_16x16x32_bf16 v[26:29], v[238:241], v[206:209], v[26:29]
	v_mfma_f32_16x16x32_bf16 v[18:21], v[226:229], v[210:213], v[18:21]
	v_mfma_f32_16x16x32_bf16 v[18:21], v[230:233], v[214:217], v[18:21]
	v_mfma_f32_16x16x32_bf16 v[10:13], v[234:237], v[210:213], v[10:13]
	v_mfma_f32_16x16x32_bf16 v[10:13], v[238:241], v[214:217], v[10:13]
	v_mfma_f32_16x16x32_bf16 v[6:9], v[226:229], v[218:221], v[6:9]
	v_mfma_f32_16x16x32_bf16 v[6:9], v[230:233], v[222:225], v[6:9]
	v_mfma_f32_16x16x32_bf16 v[2:5], v[234:237], v[218:221], v[2:5]
	v_mfma_f32_16x16x32_bf16 v[2:5], v[238:241], v[222:225], v[2:5]
	s_setprio 0
	s_add_i32 s98, s98, 2
	s_add_u32 s35, s35, 0x100
	s_addc_u32 s50, s50, 0
	s_add_u32 s0, s0, 0x100
	s_addc_u32 s1, s1, 0
	s_cmp_gt_u32 s98, 61
	s_barrier
	s_cbranch_scc0 .LBB0_627
	s_and_b64 vcc, exec, s[40:41]
	s_cbranch_vccz .LBB0_630
	s_barrier
